# norm<1> row loops: next-row loads prefetched into spare VGPRs (on top of K-loop barrier/priority edit)
# baseline (speedup 1.0000x reference)
; #define LAS __attribute__((address_space(3)))
; template <int MODE> ...
;     ...
;     __syncthreads();
; #pragma unroll
;     for (int i = 0; i < 2; ++i) { const int o = 4 * (tid + NTHREADS * i);
;         if (MODE != 0) { *(LAS f32x4*)(GP + o) = *(const f32x4*)(gpost + o); const f32x4 g = *(const f32x4*)(gprev + o); *(LAS f32x4*)(GI + o) = (f32x4){1.f / g.x, 1.f / g.y, 1.f / g.z, 1.f / g.w}; }
;         if (MODE != 2) *(LAS f32x4*)(GN + o) = *(const f32x4*)(gpre + o); }
;     __syncthreads();
.LBB0_772:
	s_cmp_gt_i32 s36, 6
	s_cselect_b64 s[6:7], -1, 0
	s_xor_b64 s[4:5], s[4:5], -1
	s_or_b64 s[4:5], s[6:7], s[4:5]
	s_and_b64 vcc, exec, s[4:5]
	s_cbranch_vccnz .LBB0_778
	s_mov_b64 s[12:13], 0
	v_mbcnt_lo_u32_b32 v2, -1, 0
	v_mbcnt_hi_u32_b32 v2, -1, v2
	s_load_dwordx4 s[4:7], s[0:1], 0x10
	s_load_dwordx2 s[8:9], s[0:1], 0x70
	v_lshlrev_b32_e32 v0, 2, v2
	v_lshl_add_u32 v24, s89, 8, v0
	v_ashrrev_i32_e32 v25, 31, v24
	v_lshlrev_b64 v[12:13], 2, v[24:25]
	v_add_u32_e32 v16, 0x800, v24
	s_waitcnt lgkmcnt(0)
	v_lshl_add_u64 v[8:9], s[4:5], 0, v[12:13]
	v_ashrrev_i32_e32 v17, 31, v16
	s_waitcnt vmcnt(0)
	s_barrier
	v_lshl_add_u64 v[4:5], s[6:7], 0, v[12:13]
	global_load_dwordx4 v[8:11], v[8:9], off
	v_lshl_add_u64 v[12:13], s[8:9], 0, v[12:13]
	v_lshlrev_b64 v[26:27], 2, v[16:17]
	global_load_dwordx4 v[4:7], v[4:5], off
	v_lshl_add_u64 v[16:17], s[6:7], 0, v[26:27]
	global_load_dwordx4 v[12:15], v[12:13], off
	v_lshl_add_u64 v[20:21], s[4:5], 0, v[26:27]
	global_load_dwordx4 v[16:19], v[16:17], off
	v_lshl_add_u32 v1, v24, 2, 0
	global_load_dwordx4 v[20:23], v[20:21], off
	v_lshl_add_u64 v[24:25], s[8:9], 0, v[26:27]
	global_load_dwordx4 v[24:27], v[24:25], off
	s_cmpk_gt_i32 s40, 0x1fff
	s_waitcnt vmcnt(5)
	v_div_scale_f32 v3, s[4:5], v8, v8, 1.0
	v_div_scale_f32 v29, s[8:9], v11, v11, 1.0
	s_waitcnt vmcnt(4)
	ds_write_b128 v1, v[4:7]
	v_div_scale_f32 v5, s[4:5], v9, v9, 1.0
	s_waitcnt vmcnt(3)
	ds_write_b128 v1, v[12:15] offset:16384
	v_rcp_f32_e32 v12, v3
	v_div_scale_f32 v7, s[6:7], v10, v10, 1.0
	v_rcp_f32_e32 v13, v5
	s_waitcnt vmcnt(2)
	ds_write_b128 v1, v[16:19] offset:8192
	s_waitcnt vmcnt(1)
	v_div_scale_f32 v16, s[10:11], v20, v20, 1.0
	v_rcp_f32_e32 v14, v7
	v_rcp_f32_e32 v19, v16
	v_rcp_f32_e32 v15, v29
	v_fma_f32 v32, -v3, v12, 1.0
	v_div_scale_f32 v4, vcc, 1.0, v8, 1.0
	v_fma_f32 v33, -v5, v13, 1.0
	v_fmac_f32_e32 v12, v32, v12
	v_div_scale_f32 v6, s[4:5], 1.0, v9, 1.0
	v_fma_f32 v34, -v7, v14, 1.0
	v_fmac_f32_e32 v13, v33, v13
	v_fma_f32 v32, -v16, v19, 1.0
	v_mul_f32_e32 v33, v4, v12
	v_div_scale_f32 v28, s[6:7], 1.0, v10, 1.0
	v_fma_f32 v35, -v29, v15, 1.0
	v_fmac_f32_e32 v14, v34, v14
	v_mul_f32_e32 v34, v6, v13
	v_fmac_f32_e32 v19, v32, v19
	v_fma_f32 v32, -v3, v33, v4
	v_div_scale_f32 v30, s[8:9], 1.0, v11, 1.0
	v_fmac_f32_e32 v15, v35, v15
	v_mul_f32_e32 v35, v28, v14
	v_fma_f32 v37, -v5, v34, v6
	v_fmac_f32_e32 v33, v32, v12
	v_div_scale_f32 v17, s[10:11], 1.0, v20, 1.0
	v_mul_f32_e32 v36, v30, v15
	v_fma_f32 v38, -v7, v35, v28
	v_fmac_f32_e32 v34, v37, v13
	v_fma_f32 v3, -v3, v33, v4
	v_div_scale_f32 v18, s[14:15], v21, v21, 1.0
	v_fma_f32 v39, -v29, v36, v30
	v_mul_f32_e32 v40, v17, v19
	v_fmac_f32_e32 v35, v38, v14
	v_fma_f32 v5, -v5, v34, v6
	v_div_fmas_f32 v3, v3, v12, v33
	s_mov_b64 vcc, s[4:5]
	v_rcp_f32_e32 v31, v18
	v_fmac_f32_e32 v36, v39, v15
	v_fma_f32 v32, -v16, v40, v17
	v_fma_f32 v6, -v7, v35, v28
	v_div_fixup_f32 v4, v3, v8, 1.0
	v_div_fmas_f32 v3, v5, v13, v34
	s_mov_b64 vcc, s[6:7]
	v_fma_f32 v7, -v29, v36, v30
	v_fmac_f32_e32 v40, v32, v19
	v_div_fixup_f32 v5, v3, v9, 1.0
	v_div_fmas_f32 v3, v6, v14, v35
	s_mov_b64 vcc, s[8:9]
	v_fma_f32 v12, -v16, v40, v17
	v_div_fixup_f32 v6, v3, v10, 1.0
	v_div_fmas_f32 v3, v7, v15, v36
	s_mov_b64 vcc, s[10:11]
	v_div_fixup_f32 v7, v3, v11, 1.0
	v_div_fmas_f32 v3, v12, v19, v40
	ds_write_b128 v1, v[4:7] offset:32768
	v_div_fixup_f32 v4, v3, v20, 1.0
	v_fma_f32 v3, -v18, v31, 1.0
	v_fmac_f32_e32 v31, v3, v31
	v_div_scale_f32 v3, vcc, 1.0, v21, 1.0
	v_mul_f32_e32 v5, v3, v31
	v_fma_f32 v6, -v18, v5, v3
	v_fmac_f32_e32 v5, v6, v31
	v_div_scale_f32 v6, s[4:5], v22, v22, 1.0
	v_rcp_f32_e32 v7, v6
	v_fma_f32 v3, -v18, v5, v3
	v_div_fmas_f32 v3, v3, v31, v5
	v_div_fixup_f32 v5, v3, v21, 1.0
	v_fma_f32 v3, -v6, v7, 1.0
	v_fmac_f32_e32 v7, v3, v7
	v_div_scale_f32 v3, vcc, 1.0, v22, 1.0
	v_mul_f32_e32 v8, v3, v7
	v_fma_f32 v9, -v6, v8, v3
	v_fmac_f32_e32 v8, v9, v7
	v_div_scale_f32 v9, s[4:5], v23, v23, 1.0
	v_rcp_f32_e32 v10, v9
	v_fma_f32 v3, -v6, v8, v3
	v_div_fmas_f32 v3, v3, v7, v8
	v_div_fixup_f32 v6, v3, v22, 1.0
	v_fma_f32 v3, -v9, v10, 1.0
	v_fmac_f32_e32 v10, v3, v10
	v_div_scale_f32 v3, vcc, 1.0, v23, 1.0
	v_mul_f32_e32 v7, v3, v10
	v_fma_f32 v8, -v9, v7, v3
	v_fmac_f32_e32 v7, v8, v10
	v_fma_f32 v3, -v9, v7, v3
	v_div_fmas_f32 v3, v3, v10, v7
	v_div_fixup_f32 v7, v3, v23, 1.0
	ds_write_b128 v1, v[4:7] offset:40960
	s_waitcnt vmcnt(0)
	ds_write_b128 v1, v[24:27] offset:24576
	s_waitcnt lgkmcnt(0)
	s_barrier
; #define LAS __attribute__((address_space(3)))
; __device__ __forceinline__ unsigned pk2(float lo, float hi) { const f32x2c v = {lo, hi}; return __builtin_bit_cast(unsigned, __builtin_convertvector(v, bf16x2c)); }
; template <int MODE> ...
;     ...
;     const int lo4 = 4 * lane;
; #pragma unroll 1
;     for (int row = gw; row < SEQ; row += NGW) {
;         asm volatile("" ::: "memory");
;         if (MODE == 0) {
;             const float* xr = xin + (size_t)row * DM; bf16* nw = xn_out + (size_t)row * DM;
;             f32x4 xv[16]; float ss = 0.f;
; #pragma unroll
;             for (int j = 0; j < 16; ++j) { xv[j] = *(const f32x4*)(xr + lo4 + 256 * j); ss += xv[j].x * xv[j].x + xv[j].y * xv[j].y + xv[j].z * xv[j].z + xv[j].w * xv[j].w; }
;             const float rstd = rsqrtf(wave_sum(ss) * (1.f / DM) + EPS);
;             if (lane == 0) rs_out[row] = rstd;
;             asm volatile("" ::: "memory");
; #pragma unroll
;             for (int j = 0; j < 16; ++j) { const f32x4 g = *(const LAS f32x4*)(GN + lo4 + 256 * j);
;                 v2u w; w.x = pk2(xv[j].x * rstd * g.x, xv[j].y * rstd * g.y); w.y = pk2(xv[j].z * rstd * g.z, xv[j].w * rstd * g.w);
;                 *(v2u*)(nw + lo4 + 256 * j) = w; }
;         } else {
;             const bf16* pr = xn + (size_t)row * DM; bf16* pw_out = xn_out + (size_t)row * DM; const bf16* hr = hb + (size_t)row * DM;
;             v2u pw[16], hw[16]; float ss = 0.f;
; #pragma unroll
;             for (int j = 0; j < 16; ++j) { pw[j] = *(const v2u*)(pr + lo4 + 256 * j); hw[j] = *(const v2u*)(hr + lo4 + 256 * j); }
;             const float ri = 1.f / rs[row];
	s_cbranch_scc1 .LBB0_778
	s_load_dwordx2 s[6:7], s[0:1], 0xe8
	s_ashr_i32 s41, s40, 31
	s_lshl_b64 s[8:9], s[40:41], 2
	v_ashrrev_i32_e32 v1, 31, v0
	v_cmp_eq_u32_e64 s[4:5], 0, v2
	s_waitcnt lgkmcnt(0)
	s_add_u32 s8, s6, s8
	s_addc_u32 s9, s7, s9
	s_add_u32 s64, s8, 0x2c0000
	s_addc_u32 s65, s9, 0
	s_ashr_i32 s39, s38, 31
	s_lshl_b64 s[8:9], s[38:39], 2
	s_lshl_b64 s[10:11], s[40:41], 13
	s_add_u32 s6, s6, s10
	s_addc_u32 s7, s7, s11
	v_mbcnt_lo_u32_b32 v2, -1, 0
	v_lshl_add_u32 v71, v0, 2, 0
	v_lshl_add_u64 v[0:1], v[0:1], 1, s[6:7]
	s_lshl_b64 s[10:11], s[38:39], 13
	s_mov_b64 s[14:15], 0x3000000
	s_mov_b64 s[18:19], 0x3000200
	s_mov_b64 s[20:21], 0x3000400
	s_mov_b64 s[22:23], 0x3000600
	s_mov_b64 s[24:25], 0x3000800
	s_mov_b64 s[26:27], 0x3000a00
	s_mov_b64 s[42:43], 0x3000c00
	s_mov_b64 s[44:45], 0x3000e00
	s_mov_b64 s[46:47], 0x3001000
	s_mov_b32 s39, 0x3001000
	s_mov_b32 s41, 0x7001000
	s_mov_b64 s[48:49], 0x3001200
	s_mov_b64 s[50:51], 0x3001400
	s_mov_b64 s[52:53], 0x3001600
	s_mov_b64 s[54:55], 0x3001800
	s_mov_b64 s[56:57], 0x3001a00
	s_mov_b64 s[58:59], 0x3001c00
	s_mov_b64 s[60:61], 0x3001e00
	v_mov_b32_e32 v98, 0
	v_mov_b32_e32 v99, 0x358637bd
	s_mov_b32 s66, 0x800000
	v_mbcnt_hi_u32_b32 v100, -1, v2
	s_mov_b32 s67, s40
	v_lshl_add_u64 v[214:215], v[0:1], 0, s[12:13]
	s_add_u32 s100, s64, s12
	s_addc_u32 s101, s65, s13
	v_add_co_u32_e32 v206, vcc, 0x3000000, v214
	s_nop 1
	v_addc_co_u32_e32 v207, vcc, 0, v215, vcc
	v_add_co_u32_e32 v208, vcc, 0x7000000, v214
	s_nop 1
	v_addc_co_u32_e32 v209, vcc, 0, v215, vcc
	v_add_co_u32_e32 v210, vcc, s39, v214
	s_nop 1
	v_addc_co_u32_e32 v211, vcc, 0, v215, vcc
	v_add_co_u32_e32 v212, vcc, s41, v214
	s_nop 1
	v_addc_co_u32_e32 v213, vcc, 0, v215, vcc
	global_load_dwordx2 v[198:199], v[208:209], off
	global_load_dwordx2 v[192:193], v[208:209], off offset:512
	global_load_dwordx2 v[190:191], v[208:209], off offset:1024
	global_load_dwordx2 v[186:187], v[208:209], off offset:1536
	global_load_dwordx2 v[182:183], v[208:209], off offset:2048
	global_load_dwordx2 v[180:181], v[208:209], off offset:2560
	global_load_dwordx2 v[176:177], v[208:209], off offset:3072
	global_load_dwordx2 v[168:169], v[210:211], off
	global_load_dwordx2 v[164:165], v[210:211], off offset:512
	global_load_dwordx2 v[160:161], v[210:211], off offset:1024
	global_load_dwordx2 v[156:157], v[210:211], off offset:1536
	global_load_dwordx2 v[170:171], v[212:213], off
	global_load_dwordx2 v[166:167], v[212:213], off offset:512
	global_load_dwordx2 v[162:163], v[212:213], off offset:1024
	global_load_dwordx2 v[158:159], v[212:213], off offset:1536
	global_load_dwordx2 v[172:173], v[208:209], off offset:3584
	global_load_dwordx2 v[152:153], v[210:211], off offset:2048
	global_load_dwordx2 v[148:149], v[210:211], off offset:2560
	global_load_dwordx2 v[144:145], v[210:211], off offset:3072
	global_load_dwordx2 v[140:141], v[210:211], off offset:3584
	global_load_dwordx2 v[154:155], v[212:213], off offset:2048
	global_load_dwordx2 v[150:151], v[212:213], off offset:2560
	global_load_dwordx2 v[146:147], v[212:213], off offset:3072
	global_load_dwordx2 v[142:143], v[212:213], off offset:3584
	global_load_dword v216, v98, s[100:101]
	global_load_dwordx2 v[202:203], v[206:207], off
	global_load_dwordx2 v[200:201], v[206:207], off offset:512
	global_load_dwordx2 v[196:197], v[206:207], off offset:1024
	global_load_dwordx2 v[194:195], v[206:207], off offset:1536
	global_load_dwordx2 v[188:189], v[206:207], off offset:2048
	global_load_dwordx2 v[184:185], v[206:207], off offset:2560
	global_load_dwordx2 v[178:179], v[206:207], off offset:3072
	global_load_dwordx2 v[174:175], v[206:207], off offset:3584
	s_waitcnt vmcnt(0)
	s_branch .Lnpf_body_0

; template <int MODE> ...
;     ...
;             const bf16* pr = xn + (size_t)row * DM; bf16* pw_out = xn_out + (size_t)row * DM; const bf16* hr = hb + (size_t)row * DM;
;             v2u pw[16], hw[16]; float ss = 0.f;
; #pragma unroll
;             for (int j = 0; j < 16; ++j) { pw[j] = *(const v2u*)(pr + lo4 + 256 * j); hw[j] = *(const v2u*)(hr + lo4 + 256 * j); }
.LBB0_776:
	s_waitcnt vmcnt(16)
.Lnpf_body_0:
	v_mov_b32_e32 v2, v140
	v_mov_b32_e32 v3, v141
	v_mov_b32_e32 v4, v142
	v_mov_b32_e32 v5, v143
	v_mov_b32_e32 v6, v144
	v_mov_b32_e32 v7, v145
	v_mov_b32_e32 v8, v146
	v_mov_b32_e32 v9, v147
	v_mov_b32_e32 v10, v148
	v_mov_b32_e32 v11, v149
	v_mov_b32_e32 v12, v150
	v_mov_b32_e32 v13, v151
	v_mov_b32_e32 v14, v152
	v_mov_b32_e32 v15, v153
	v_mov_b32_e32 v16, v154
	v_mov_b32_e32 v17, v155
	v_mov_b32_e32 v18, v156
	v_mov_b32_e32 v19, v157
	v_mov_b32_e32 v20, v158
	v_mov_b32_e32 v21, v159
	v_mov_b32_e32 v22, v160
	v_mov_b32_e32 v23, v161
	v_mov_b32_e32 v24, v162
	v_mov_b32_e32 v25, v163
	v_mov_b32_e32 v26, v164
	v_mov_b32_e32 v27, v165
	v_mov_b32_e32 v28, v166
	v_mov_b32_e32 v29, v167
	v_mov_b32_e32 v30, v168
	v_mov_b32_e32 v31, v169
	v_mov_b32_e32 v32, v170
	v_mov_b32_e32 v33, v171
	v_mov_b32_e32 v34, v172
	v_mov_b32_e32 v35, v173
	v_mov_b32_e32 v36, v174
	v_mov_b32_e32 v37, v175
	v_mov_b32_e32 v38, v176
	v_mov_b32_e32 v39, v177
	v_mov_b32_e32 v40, v178
	v_mov_b32_e32 v41, v179
	v_mov_b32_e32 v42, v180
	v_mov_b32_e32 v43, v181
	v_mov_b32_e32 v44, v182
	v_mov_b32_e32 v45, v183
	v_mov_b32_e32 v46, v184
	v_mov_b32_e32 v47, v185
	v_mov_b32_e32 v48, v186
	v_mov_b32_e32 v49, v187
	v_mov_b32_e32 v50, v188
	v_mov_b32_e32 v51, v189
	v_mov_b32_e32 v52, v190
	v_mov_b32_e32 v53, v191
	v_mov_b32_e32 v54, v192
	v_mov_b32_e32 v55, v193
	v_mov_b32_e32 v56, v194
	v_mov_b32_e32 v57, v195
	v_mov_b32_e32 v58, v196
	v_mov_b32_e32 v59, v197
	v_mov_b32_e32 v60, v198
	v_mov_b32_e32 v61, v199
	v_mov_b32_e32 v62, v200
	v_mov_b32_e32 v63, v201
	v_mov_b32_e32 v64, v202
	v_mov_b32_e32 v65, v203
	v_mov_b32_e32 v78, v216
	s_add_i32 s98, s67, s38
	s_cmpk_lt_i32 s98, 0x2000
	s_cbranch_scc0 .Lnpf_skip_0
	v_lshl_add_u64 v[214:215], v[0:1], 0, s[10:11]
	v_lshl_add_u64 v[214:215], v[214:215], 0, s[12:13]
	s_add_u32 s100, s64, s8
	s_addc_u32 s101, s65, s9
	s_add_u32 s100, s100, s12
	s_addc_u32 s101, s101, s13
	v_add_co_u32_e32 v206, vcc, 0x3000000, v214
	s_nop 1
	v_addc_co_u32_e32 v207, vcc, 0, v215, vcc
	v_add_co_u32_e32 v208, vcc, 0x7000000, v214
	s_nop 1
	v_addc_co_u32_e32 v209, vcc, 0, v215, vcc
	v_add_co_u32_e32 v210, vcc, s39, v214
	s_nop 1
	v_addc_co_u32_e32 v211, vcc, 0, v215, vcc
	v_add_co_u32_e32 v212, vcc, s41, v214
	s_nop 1
	v_addc_co_u32_e32 v213, vcc, 0, v215, vcc
	global_load_dwordx2 v[198:199], v[208:209], off
	global_load_dwordx2 v[192:193], v[208:209], off offset:512
	global_load_dwordx2 v[190:191], v[208:209], off offset:1024
	global_load_dwordx2 v[186:187], v[208:209], off offset:1536
	global_load_dwordx2 v[182:183], v[208:209], off offset:2048
	global_load_dwordx2 v[180:181], v[208:209], off offset:2560
	global_load_dwordx2 v[176:177], v[208:209], off offset:3072
	global_load_dwordx2 v[168:169], v[210:211], off
	global_load_dwordx2 v[164:165], v[210:211], off offset:512
	global_load_dwordx2 v[160:161], v[210:211], off offset:1024
	global_load_dwordx2 v[156:157], v[210:211], off offset:1536
	global_load_dwordx2 v[170:171], v[212:213], off
	global_load_dwordx2 v[166:167], v[212:213], off offset:512
	global_load_dwordx2 v[162:163], v[212:213], off offset:1024
	global_load_dwordx2 v[158:159], v[212:213], off offset:1536
	global_load_dwordx2 v[172:173], v[208:209], off offset:3584
	global_load_dwordx2 v[152:153], v[210:211], off offset:2048
	global_load_dwordx2 v[148:149], v[210:211], off offset:2560
	global_load_dwordx2 v[144:145], v[210:211], off offset:3072
	global_load_dwordx2 v[140:141], v[210:211], off offset:3584
	global_load_dwordx2 v[154:155], v[212:213], off offset:2048
	global_load_dwordx2 v[150:151], v[212:213], off offset:2560
	global_load_dwordx2 v[146:147], v[212:213], off offset:3072
	global_load_dwordx2 v[142:143], v[212:213], off offset:3584
	global_load_dword v216, v98, s[100:101]
	global_load_dwordx2 v[202:203], v[206:207], off
	global_load_dwordx2 v[200:201], v[206:207], off offset:512
	global_load_dwordx2 v[196:197], v[206:207], off offset:1024
	global_load_dwordx2 v[194:195], v[206:207], off offset:1536
	global_load_dwordx2 v[188:189], v[206:207], off offset:2048
	global_load_dwordx2 v[184:185], v[206:207], off offset:2560
	global_load_dwordx2 v[178:179], v[206:207], off offset:3072
	global_load_dwordx2 v[174:175], v[206:207], off offset:3584
; __device__ __forceinline__ float bflo(unsigned w) { return __uint_as_float(w << 16); }
; __device__ __forceinline__ float bfhi(unsigned w) { return __uint_as_float(w & 0xffff0000u); }
; template <int MODE> ...
;     ...
;             const bf16* pr = xn + (size_t)row * DM; bf16* pw_out = xn_out + (size_t)row * DM; const bf16* hr = hb + (size_t)row * DM;
;             v2u pw[16], hw[16]; float ss = 0.f;
; #pragma unroll
;             for (int j = 0; j < 16; ++j) { pw[j] = *(const v2u*)(pr + lo4 + 256 * j); hw[j] = *(const v2u*)(hr + lo4 + 256 * j); }
;             const float ri = 1.f / rs[row];
; #pragma unroll
;             for (int j = 0; j < 16; ++j) { const float a = bflo(hw[j].x), b = bfhi(hw[j].x), c = bflo(hw[j].y), d = bfhi(hw[j].y); ss += a * a + b * b + c * c + d * d; }
;             const float rstd = rsqrtf(wave_sum(ss) * (1.f / DM) + EPS);
.Lnpf_skip_0:
	v_lshl_add_u64 v[66:67], v[0:1], 0, s[12:13]
	s_add_u32 s62, s64, s12
	s_addc_u32 s63, s65, s13
	v_and_b32_e32 v69, 0xffff0000, v60
	v_and_b32_e32 v74, 0xffff0000, v54
	v_lshlrev_b32_e32 v68, 16, v60
	v_lshlrev_b32_e32 v73, 16, v54
	v_mul_f32_e32 v69, v69, v69
	v_mul_f32_e32 v74, v74, v74
	v_lshlrev_b32_e32 v70, 16, v61
	v_lshlrev_b32_e32 v75, 16, v55
	v_and_b32_e32 v79, 0xffff0000, v52
	v_fmac_f32_e32 v69, v68, v68
	v_fmac_f32_e32 v74, v73, v73
	v_and_b32_e32 v72, 0xffff0000, v61
	v_and_b32_e32 v76, 0xffff0000, v55
	v_lshlrev_b32_e32 v77, 16, v52
	v_and_b32_e32 v83, 0xffff0000, v48
	v_and_b32_e32 v87, 0xffff0000, v44
	v_mul_f32_e32 v79, v79, v79
	v_fmac_f32_e32 v69, v70, v70
	v_fmac_f32_e32 v74, v75, v75
	v_lshlrev_b32_e32 v80, 16, v53
	v_lshlrev_b32_e32 v82, 16, v48
	v_lshlrev_b32_e32 v86, 16, v44
	v_mul_f32_e32 v83, v83, v83
	v_fmac_f32_e32 v79, v77, v77
	v_fmac_f32_e32 v69, v72, v72
	v_fmac_f32_e32 v74, v76, v76
	v_mul_f32_e32 v72, v87, v87
	v_and_b32_e32 v81, 0xffff0000, v53
	v_lshlrev_b32_e32 v84, 16, v49
	v_fmac_f32_e32 v83, v82, v82
	v_fmac_f32_e32 v79, v80, v80
	v_add_f32_e32 v68, v69, v74
	v_lshlrev_b32_e32 v69, 16, v45
	v_fmac_f32_e32 v72, v86, v86
	v_and_b32_e32 v85, 0xffff0000, v49
	v_fmac_f32_e32 v83, v84, v84
	v_fmac_f32_e32 v79, v81, v81
	v_and_b32_e32 v70, 0xffff0000, v45
	v_fmac_f32_e32 v72, v69, v69
	v_fmac_f32_e32 v83, v85, v85
	v_add_f32_e32 v68, v68, v79
	v_fmac_f32_e32 v72, v70, v70
	v_and_b32_e32 v70, 0xffff0000, v42
	v_add_f32_e32 v68, v68, v83
	v_lshlrev_b32_e32 v69, 16, v42
	v_mul_f32_e32 v70, v70, v70
	v_add_f32_e32 v68, v68, v72
	v_lshlrev_b32_e32 v72, 16, v43
	v_fmac_f32_e32 v70, v69, v69
	v_and_b32_e32 v73, 0xffff0000, v43
	v_fmac_f32_e32 v70, v72, v72
	v_fmac_f32_e32 v70, v73, v73
	v_add_f32_e32 v68, v68, v70
	v_and_b32_e32 v70, 0xffff0000, v38
	v_lshlrev_b32_e32 v69, 16, v38
	v_mul_f32_e32 v70, v70, v70
	v_lshlrev_b32_e32 v72, 16, v39
	v_fmac_f32_e32 v70, v69, v69
	v_and_b32_e32 v73, 0xffff0000, v39
	v_fmac_f32_e32 v70, v72, v72
	v_fmac_f32_e32 v70, v73, v73
	v_add_f32_e32 v68, v68, v70
	v_and_b32_e32 v70, 0xffff0000, v34
	v_lshlrev_b32_e32 v69, 16, v34
	v_mul_f32_e32 v70, v70, v70
	v_lshlrev_b32_e32 v72, 16, v35
	v_fmac_f32_e32 v70, v69, v69
	v_and_b32_e32 v73, 0xffff0000, v35
	v_fmac_f32_e32 v70, v72, v72
	v_fmac_f32_e32 v70, v73, v73
	v_add_f32_e32 v68, v68, v70
	v_and_b32_e32 v70, 0xffff0000, v32
	v_lshlrev_b32_e32 v69, 16, v32
	v_mul_f32_e32 v70, v70, v70
	v_lshlrev_b32_e32 v72, 16, v33
	v_fmac_f32_e32 v70, v69, v69
	v_and_b32_e32 v73, 0xffff0000, v33
	v_fmac_f32_e32 v70, v72, v72
	v_fmac_f32_e32 v70, v73, v73
	v_add_f32_e32 v68, v68, v70
	v_and_b32_e32 v70, 0xffff0000, v28
	v_lshlrev_b32_e32 v69, 16, v28
	v_mul_f32_e32 v70, v70, v70
	v_lshlrev_b32_e32 v72, 16, v29
	v_fmac_f32_e32 v70, v69, v69
	v_and_b32_e32 v73, 0xffff0000, v29
	v_fmac_f32_e32 v70, v72, v72
	v_fmac_f32_e32 v70, v73, v73
	v_add_f32_e32 v68, v68, v70
	v_and_b32_e32 v70, 0xffff0000, v24
	v_lshlrev_b32_e32 v69, 16, v24
	v_mul_f32_e32 v70, v70, v70
	v_lshlrev_b32_e32 v72, 16, v25
	v_fmac_f32_e32 v70, v69, v69
	v_and_b32_e32 v73, 0xffff0000, v25
	v_fmac_f32_e32 v70, v72, v72
	v_fmac_f32_e32 v70, v73, v73
	v_add_f32_e32 v68, v68, v70
	v_and_b32_e32 v70, 0xffff0000, v20
	v_lshlrev_b32_e32 v69, 16, v20
	v_mul_f32_e32 v70, v70, v70
	v_lshlrev_b32_e32 v72, 16, v21
	v_fmac_f32_e32 v70, v69, v69
	v_and_b32_e32 v73, 0xffff0000, v21
	v_fmac_f32_e32 v70, v72, v72
	v_fmac_f32_e32 v70, v73, v73
	v_and_b32_e32 v73, 0xffff0000, v12
	v_and_b32_e32 v72, 0xffff0000, v16
	v_add_f32_e32 v70, v68, v70
	v_lshlrev_b32_e32 v69, 16, v12
	v_lshlrev_b32_e32 v68, 16, v16
	v_pk_mul_f32 v[72:73], v[72:73], v[72:73]
	v_lshlrev_b32_e32 v75, 16, v13
	v_lshlrev_b32_e32 v74, 16, v17
	v_pk_fma_f32 v[68:69], v[68:69], v[68:69], v[72:73]
	v_and_b32_e32 v77, 0xffff0000, v13
	v_and_b32_e32 v76, 0xffff0000, v17
	v_pk_fma_f32 v[68:69], v[74:75], v[74:75], v[68:69]
	v_and_b32_e32 v73, 0xffff0000, v4
	v_pk_fma_f32 v[68:69], v[76:77], v[76:77], v[68:69]
	v_and_b32_e32 v72, 0xffff0000, v8
	v_add_f32_e32 v68, v70, v68
	v_add_f32_e32 v70, v68, v69
	v_lshlrev_b32_e32 v69, 16, v4
	v_lshlrev_b32_e32 v68, 16, v8
	v_pk_mul_f32 v[72:73], v[72:73], v[72:73]
	v_lshlrev_b32_e32 v75, 16, v5
	v_lshlrev_b32_e32 v74, 16, v9
	v_pk_fma_f32 v[68:69], v[68:69], v[68:69], v[72:73]
	v_and_b32_e32 v77, 0xffff0000, v5
	v_and_b32_e32 v76, 0xffff0000, v9
	v_pk_fma_f32 v[68:69], v[74:75], v[74:75], v[68:69]
	v_pk_fma_f32 v[68:69], v[76:77], v[76:77], v[68:69]
	v_div_scale_f32 v77, s[6:7], v78, v78, 1.0
	v_add_f32_e32 v68, v70, v68
	v_add_f32_e32 v68, v68, v69
	v_and_b32_e32 v69, 64, v100
	v_add_u32_e32 v69, 64, v69
	v_xor_b32_e32 v70, 1, v100
	v_cmp_lt_i32_e32 vcc, v70, v69
	v_rcp_f32_e32 v79, v77
	v_lshlrev_b32_e32 v86, 16, v60
	v_cndmask_b32_e32 v70, v100, v70, vcc
	v_lshlrev_b32_e32 v70, 2, v70
	ds_bpermute_b32 v72, v70, v68
	v_fma_f32 v80, -v77, v79, 1.0
	v_fmac_f32_e32 v79, v80, v79
	s_waitcnt lgkmcnt(0)
	v_add_f32_e32 v68, v68, v72
	v_xor_b32_e32 v72, 2, v100
	v_cmp_lt_i32_e32 vcc, v72, v69
	s_nop 1
	v_cndmask_b32_e32 v72, v100, v72, vcc
	v_lshlrev_b32_e32 v72, 2, v72
	ds_bpermute_b32 v73, v72, v68
	s_waitcnt lgkmcnt(0)
	v_add_f32_e32 v68, v68, v73
	v_xor_b32_e32 v73, 4, v100
	v_cmp_lt_i32_e32 vcc, v73, v69
	s_nop 1
	v_cndmask_b32_e32 v73, v100, v73, vcc
	v_lshlrev_b32_e32 v73, 2, v73
	ds_bpermute_b32 v74, v73, v68
	s_waitcnt lgkmcnt(0)
	v_add_f32_e32 v68, v68, v74
	v_xor_b32_e32 v74, 8, v100
	v_cmp_lt_i32_e32 vcc, v74, v69
	s_nop 1
	v_cndmask_b32_e32 v74, v100, v74, vcc
	v_lshlrev_b32_e32 v74, 2, v74
	ds_bpermute_b32 v75, v74, v68
	s_waitcnt lgkmcnt(0)
; #define LAS __attribute__((address_space(3)))
; __device__ __forceinline__ float bflo(unsigned w) { return __uint_as_float(w << 16); }
; __device__ __forceinline__ float bfhi(unsigned w) { return __uint_as_float(w & 0xffff0000u); }
; #define LAUNDER_ROW(pw, hw) do { LAUNDER8(pw, 0); LAUNDER8(pw, 8); LAUNDER8(hw, 0); LAUNDER8(hw, 8); } while (0)
; template <int MODE> ...
;     ...
;             const float ri = 1.f / rs[row];
; #pragma unroll
;             for (int j = 0; j < 16; ++j) { const float a = bflo(hw[j].x), b = bfhi(hw[j].x), c = bflo(hw[j].y), d = bfhi(hw[j].y); ss += a * a + b * b + c * c + d * d; }
;             const float rstd = rsqrtf(wave_sum(ss) * (1.f / DM) + EPS);
;             asm volatile("" ::: "memory");
;             LAUNDER_ROW(pw, hw);
;             float ss2 = 0.f;
; #pragma unroll
;             for (int j = 0; j < 16; ++j) { const f32x4 g = *(const LAS f32x4*)(GP + lo4 + 256 * j), gi = *(const LAS f32x4*)(GI + lo4 + 256 * j);
;                 f32x4 x;
;                 x.x = bflo(pw[j].x) * ri * gi.x + bflo(hw[j].x) * rstd * g.x; x.y = bfhi(pw[j].x) * ri * gi.y + bfhi(hw[j].x) * rstd * g.y;
;                 x.z = bflo(pw[j].y) * ri * gi.z + bflo(hw[j].y) * rstd * g.z; x.w = bfhi(pw[j].y) * ri * gi.w + bfhi(hw[j].y) * rstd * g.w;
;                 if (MODE == 2) *(f32x4*)(xout + (size_t)row * DM + lo4 + 256 * j) = x;
;                 else ss2 += x.x * x.x + x.y * x.y + x.z * x.z + x.w * x.w;
;                 if (j & 1) __builtin_amdgcn_sched_barrier(0); }
	v_add_f32_e32 v68, v68, v75
	v_xor_b32_e32 v75, 16, v100
	v_cmp_lt_i32_e32 vcc, v75, v69
	s_nop 1
	v_cndmask_b32_e32 v75, v100, v75, vcc
	v_lshlrev_b32_e32 v75, 2, v75
	ds_bpermute_b32 v76, v75, v68
	v_div_scale_f32 v80, vcc, 1.0, v78, 1.0
	v_mul_f32_e32 v81, v80, v79
	v_fma_f32 v82, -v77, v81, v80
	s_waitcnt lgkmcnt(0)
	v_add_f32_e32 v68, v68, v76
	v_xor_b32_e32 v76, 32, v100
	v_cmp_lt_i32_e64 s[6:7], v76, v69
	v_fmac_f32_e32 v81, v82, v79
	v_fma_f32 v77, -v77, v81, v80
	v_cndmask_b32_e64 v69, v100, v76, s[6:7]
	v_lshlrev_b32_e32 v76, 2, v69
	ds_bpermute_b32 v69, v76, v68
	s_waitcnt lgkmcnt(0)
	v_add_f32_e32 v68, v68, v69
	v_fmamk_f32 v68, v68, 0x39800000, v99
	v_mul_f32_e32 v69, 0x4b800000, v68
	v_cmp_gt_f32_e64 s[6:7], s66, v68
	s_nop 1
	v_cndmask_b32_e64 v68, v68, v69, s[6:7]
	v_rsq_f32_e32 v69, v68
	v_div_fmas_f32 v68, v77, v79, v81
	v_div_fixup_f32 v68, v68, v78, 1.0
	ds_read_b128 v[78:81], v71
	ds_read_b128 v[82:85], v71 offset:32768
	v_mul_f32_e32 v77, 0x45800000, v69
	v_cndmask_b32_e64 v69, v69, v77, s[6:7]
	v_lshlrev_b32_e32 v77, 16, v64
	v_mul_f32_e32 v90, v69, v86
	v_mul_f32_e32 v77, v68, v77
	s_waitcnt lgkmcnt(1)
	v_mul_f32_e32 v78, v78, v90
	s_waitcnt lgkmcnt(0)
	v_fmac_f32_e32 v78, v77, v82
	v_and_b32_e32 v82, 0xffff0000, v60
	v_and_b32_e32 v77, 0xffff0000, v64
	v_mul_f32_e32 v82, v69, v82
	v_mul_f32_e32 v77, v68, v77
	v_mul_f32_e32 v79, v79, v82
	v_lshlrev_b32_e32 v82, 16, v61
	v_fmac_f32_e32 v79, v77, v83
	v_lshlrev_b32_e32 v77, 16, v65
	v_mul_f32_e32 v82, v69, v82
	ds_read_b128 v[86:89], v71 offset:1024
	ds_read_b128 v[90:93], v71 offset:33792
	v_mul_f32_e32 v77, v68, v77
	v_mul_f32_e32 v80, v80, v82
	v_and_b32_e32 v82, 0xffff0000, v61
	v_fmac_f32_e32 v80, v77, v84
	v_and_b32_e32 v77, 0xffff0000, v65
	v_mul_f32_e32 v82, v69, v82
	v_mul_f32_e32 v77, v68, v77
	v_mul_f32_e32 v81, v81, v82
	v_fmac_f32_e32 v81, v77, v85
	v_mul_f32_e32 v77, v79, v79
	v_lshlrev_b32_e32 v79, 16, v54
	v_fmac_f32_e32 v77, v78, v78
	v_lshlrev_b32_e32 v78, 16, v62
	v_mul_f32_e32 v79, v69, v79
	v_fmac_f32_e32 v77, v80, v80
	v_mul_f32_e32 v78, v68, v78
	s_waitcnt lgkmcnt(1)
	v_mul_f32_e32 v79, v86, v79
	v_and_b32_e32 v80, 0xffff0000, v54
	s_waitcnt lgkmcnt(0)
	v_fmac_f32_e32 v79, v78, v90
	v_and_b32_e32 v78, 0xffff0000, v62
	v_mul_f32_e32 v80, v69, v80
	v_fmac_f32_e32 v77, v81, v81
	v_mul_f32_e32 v78, v68, v78
	v_mul_f32_e32 v80, v87, v80
	v_lshlrev_b32_e32 v81, 16, v55
	v_fmac_f32_e32 v80, v78, v91
	v_lshlrev_b32_e32 v78, 16, v63
	v_mul_f32_e32 v81, v69, v81
	v_mul_f32_e32 v78, v68, v78
	v_mul_f32_e32 v81, v88, v81
	v_and_b32_e32 v82, 0xffff0000, v55
	v_fmac_f32_e32 v81, v78, v92
	v_and_b32_e32 v78, 0xffff0000, v63
	v_mul_f32_e32 v82, v69, v82
	v_mul_f32_e32 v78, v68, v78
	v_mul_f32_e32 v82, v89, v82
	v_fmac_f32_e32 v82, v78, v93
	v_mul_f32_e32 v78, v80, v80
	v_fmac_f32_e32 v78, v79, v79
	v_fmac_f32_e32 v78, v81, v81
	v_fmac_f32_e32 v78, v82, v82
	v_add_f32_e32 v77, v77, v78
	ds_read_b128 v[78:81], v71 offset:34816
	ds_read_b128 v[82:85], v71 offset:2048
	v_lshlrev_b32_e32 v90, 16, v58
	v_mul_f32_e32 v90, v68, v90
	ds_read_b128 v[86:89], v71 offset:35840
	s_waitcnt lgkmcnt(2)
	v_mul_f32_e32 v78, v90, v78
	v_lshlrev_b32_e32 v90, 16, v52
	v_mul_f32_e32 v94, v69, v90
	s_waitcnt lgkmcnt(1)
	v_fmac_f32_e32 v78, v82, v94
	v_and_b32_e32 v82, 0xffff0000, v58
	v_mul_f32_e32 v82, v68, v82
	v_mul_f32_e32 v79, v82, v79
	v_and_b32_e32 v82, 0xffff0000, v52
	v_mul_f32_e32 v82, v69, v82
	v_fmac_f32_e32 v79, v83, v82
	v_lshlrev_b32_e32 v82, 16, v59
	v_mul_f32_e32 v82, v68, v82
	v_mul_f32_e32 v80, v82, v80
	v_lshlrev_b32_e32 v82, 16, v53
	v_mul_f32_e32 v82, v69, v82
	v_fmac_f32_e32 v80, v84, v82
	v_and_b32_e32 v82, 0xffff0000, v59
	v_mul_f32_e32 v82, v68, v82
	v_mul_f32_e32 v81, v82, v81
	v_and_b32_e32 v82, 0xffff0000, v53
	v_mul_f32_e32 v79, v79, v79
	ds_read_b128 v[90:93], v71 offset:3072
	v_mul_f32_e32 v82, v69, v82
	v_fmac_f32_e32 v79, v78, v78
	v_fmac_f32_e32 v81, v85, v82
	v_fmac_f32_e32 v79, v80, v80
	v_fmac_f32_e32 v79, v81, v81
	v_add_f32_e32 v77, v79, v77
	v_lshlrev_b32_e32 v79, 16, v48
	v_lshlrev_b32_e32 v78, 16, v56
	v_mul_f32_e32 v79, v69, v79
	v_mul_f32_e32 v78, v68, v78
	s_waitcnt lgkmcnt(0)
	v_mul_f32_e32 v79, v79, v90
	v_and_b32_e32 v80, 0xffff0000, v48
	v_fmac_f32_e32 v79, v78, v86
	v_and_b32_e32 v78, 0xffff0000, v56
	v_mul_f32_e32 v80, v69, v80
	v_mul_f32_e32 v78, v68, v78
	v_mul_f32_e32 v80, v80, v91
	v_lshlrev_b32_e32 v81, 16, v49
	v_fmac_f32_e32 v80, v78, v87
	v_lshlrev_b32_e32 v78, 16, v57
	v_mul_f32_e32 v81, v69, v81
	v_mul_f32_e32 v78, v68, v78
	v_mul_f32_e32 v81, v81, v92
	v_and_b32_e32 v82, 0xffff0000, v49
	v_fmac_f32_e32 v81, v78, v88
	v_and_b32_e32 v78, 0xffff0000, v57
	v_mul_f32_e32 v82, v69, v82
	v_mul_f32_e32 v78, v68, v78
	v_mul_f32_e32 v82, v82, v93
	v_fmac_f32_e32 v82, v78, v89
	v_mul_f32_e32 v78, v80, v80
	v_fmac_f32_e32 v78, v79, v79
	v_fmac_f32_e32 v78, v81, v81
	v_fmac_f32_e32 v78, v82, v82
	v_add_f32_e32 v77, v77, v78
	ds_read_b128 v[78:81], v71 offset:36864
	ds_read_b128 v[82:85], v71 offset:4096
	v_lshlrev_b32_e32 v90, 16, v50
	v_mul_f32_e32 v90, v68, v90
	ds_read_b128 v[86:89], v71 offset:37888
	s_waitcnt lgkmcnt(2)
	v_mul_f32_e32 v78, v90, v78
	v_lshlrev_b32_e32 v90, 16, v44
	v_mul_f32_e32 v94, v69, v90
	s_waitcnt lgkmcnt(1)
; #define LAS __attribute__((address_space(3)))
; __device__ __forceinline__ float bflo(unsigned w) { return __uint_as_float(w << 16); }
; __device__ __forceinline__ float bfhi(unsigned w) { return __uint_as_float(w & 0xffff0000u); }
; template <int MODE> ...
;     ...
;             for (int j = 0; j < 16; ++j) { const f32x4 g = *(const LAS f32x4*)(GP + lo4 + 256 * j), gi = *(const LAS f32x4*)(GI + lo4 + 256 * j);
;                 f32x4 x;
;                 x.x = bflo(pw[j].x) * ri * gi.x + bflo(hw[j].x) * rstd * g.x; x.y = bfhi(pw[j].x) * ri * gi.y + bfhi(hw[j].x) * rstd * g.y;
;                 x.z = bflo(pw[j].y) * ri * gi.z + bflo(hw[j].y) * rstd * g.z; x.w = bfhi(pw[j].y) * ri * gi.w + bfhi(hw[j].y) * rstd * g.w;
;                 if (MODE == 2) *(f32x4*)(xout + (size_t)row * DM + lo4 + 256 * j) = x;
;                 else ss2 += x.x * x.x + x.y * x.y + x.z * x.z + x.w * x.w;
;                 if (j & 1) __builtin_amdgcn_sched_barrier(0); }
	v_fmac_f32_e32 v78, v94, v82
	v_and_b32_e32 v82, 0xffff0000, v50
	v_mul_f32_e32 v82, v68, v82
	v_mul_f32_e32 v79, v82, v79
	v_and_b32_e32 v82, 0xffff0000, v44
	v_mul_f32_e32 v82, v69, v82
	v_fmac_f32_e32 v79, v82, v83
	v_lshlrev_b32_e32 v82, 16, v51
	v_mul_f32_e32 v82, v68, v82
	v_mul_f32_e32 v80, v82, v80
	v_lshlrev_b32_e32 v82, 16, v45
	v_mul_f32_e32 v82, v69, v82
	v_fmac_f32_e32 v80, v82, v84
	v_and_b32_e32 v82, 0xffff0000, v51
	v_mul_f32_e32 v82, v68, v82
	v_mul_f32_e32 v81, v82, v81
	v_and_b32_e32 v82, 0xffff0000, v45
	v_mul_f32_e32 v79, v79, v79
	ds_read_b128 v[90:93], v71 offset:5120
	v_mul_f32_e32 v82, v69, v82
	v_fmac_f32_e32 v79, v78, v78
	v_fmac_f32_e32 v81, v82, v85
	v_fmac_f32_e32 v79, v80, v80
	v_fmac_f32_e32 v79, v81, v81
	v_add_f32_e32 v77, v77, v79
	v_lshlrev_b32_e32 v79, 16, v42
	v_lshlrev_b32_e32 v78, 16, v46
	v_mul_f32_e32 v79, v69, v79
	v_mul_f32_e32 v78, v68, v78
	s_waitcnt lgkmcnt(0)
	v_mul_f32_e32 v79, v79, v90
	v_and_b32_e32 v80, 0xffff0000, v42
	v_fmac_f32_e32 v79, v78, v86
	v_and_b32_e32 v78, 0xffff0000, v46
	v_mul_f32_e32 v80, v69, v80
	v_mul_f32_e32 v78, v68, v78
	v_mul_f32_e32 v80, v80, v91
	v_lshlrev_b32_e32 v81, 16, v43
	v_fmac_f32_e32 v80, v78, v87
	v_lshlrev_b32_e32 v78, 16, v47
	v_mul_f32_e32 v81, v69, v81
	v_mul_f32_e32 v78, v68, v78
	v_mul_f32_e32 v81, v81, v92
	v_and_b32_e32 v82, 0xffff0000, v43
	v_fmac_f32_e32 v81, v78, v88
	v_and_b32_e32 v78, 0xffff0000, v47
	v_mul_f32_e32 v82, v69, v82
	v_mul_f32_e32 v78, v68, v78
	v_mul_f32_e32 v82, v82, v93
	v_fmac_f32_e32 v82, v78, v89
	v_mul_f32_e32 v78, v80, v80
	v_fmac_f32_e32 v78, v79, v79
	v_fmac_f32_e32 v78, v81, v81
	v_fmac_f32_e32 v78, v82, v82
	v_add_f32_e32 v77, v77, v78
	ds_read_b128 v[78:81], v71 offset:38912
	ds_read_b128 v[82:85], v71 offset:6144
	v_lshlrev_b32_e32 v90, 16, v40
	v_mul_f32_e32 v90, v68, v90
	ds_read_b128 v[86:89], v71 offset:39936
	s_waitcnt lgkmcnt(2)
	v_mul_f32_e32 v78, v90, v78
	v_lshlrev_b32_e32 v90, 16, v38
	v_mul_f32_e32 v94, v69, v90
	s_waitcnt lgkmcnt(1)
	v_fmac_f32_e32 v78, v94, v82
	v_and_b32_e32 v82, 0xffff0000, v40
	v_mul_f32_e32 v82, v68, v82
	v_mul_f32_e32 v79, v82, v79
	v_and_b32_e32 v82, 0xffff0000, v38
	v_mul_f32_e32 v82, v69, v82
	v_fmac_f32_e32 v79, v82, v83
	v_lshlrev_b32_e32 v82, 16, v41
	v_mul_f32_e32 v82, v68, v82
	v_mul_f32_e32 v80, v82, v80
	v_lshlrev_b32_e32 v82, 16, v39
	v_mul_f32_e32 v82, v69, v82
	v_fmac_f32_e32 v80, v82, v84
	v_and_b32_e32 v82, 0xffff0000, v41
	v_mul_f32_e32 v82, v68, v82
	v_mul_f32_e32 v81, v82, v81
	v_and_b32_e32 v82, 0xffff0000, v39
	v_mul_f32_e32 v79, v79, v79
	ds_read_b128 v[90:93], v71 offset:7168
	v_mul_f32_e32 v82, v69, v82
	v_fmac_f32_e32 v79, v78, v78
	v_fmac_f32_e32 v81, v82, v85
	v_fmac_f32_e32 v79, v80, v80
	v_fmac_f32_e32 v79, v81, v81
	v_add_f32_e32 v77, v77, v79
	v_lshlrev_b32_e32 v79, 16, v34
	v_lshlrev_b32_e32 v78, 16, v36
	v_mul_f32_e32 v79, v69, v79
	v_mul_f32_e32 v78, v68, v78
	s_waitcnt lgkmcnt(0)
	v_mul_f32_e32 v79, v79, v90
	v_and_b32_e32 v80, 0xffff0000, v34
	v_fmac_f32_e32 v79, v78, v86
	v_and_b32_e32 v78, 0xffff0000, v36
	v_mul_f32_e32 v80, v69, v80
	v_mul_f32_e32 v78, v68, v78
	v_mul_f32_e32 v80, v80, v91
	v_lshlrev_b32_e32 v81, 16, v35
	v_fmac_f32_e32 v80, v78, v87
	v_lshlrev_b32_e32 v78, 16, v37
	v_mul_f32_e32 v81, v69, v81
	v_mul_f32_e32 v78, v68, v78
	v_mul_f32_e32 v81, v81, v92
	v_and_b32_e32 v82, 0xffff0000, v35
	v_fmac_f32_e32 v81, v78, v88
	v_and_b32_e32 v78, 0xffff0000, v37
	v_mul_f32_e32 v82, v69, v82
	v_mul_f32_e32 v78, v68, v78
	v_mul_f32_e32 v82, v82, v93
	v_fmac_f32_e32 v82, v78, v89
	v_mul_f32_e32 v78, v80, v80
	v_fmac_f32_e32 v78, v79, v79
	v_fmac_f32_e32 v78, v81, v81
	v_fmac_f32_e32 v78, v82, v82
	v_add_f32_e32 v77, v77, v78
	ds_read_b128 v[78:81], v71 offset:40960
	ds_read_b128 v[82:85], v71 offset:8192
	v_lshlrev_b32_e32 v90, 16, v30
	v_mul_f32_e32 v90, v68, v90
	ds_read_b128 v[86:89], v71 offset:41984
	s_waitcnt lgkmcnt(2)
	v_mul_f32_e32 v78, v90, v78
	v_lshlrev_b32_e32 v90, 16, v32
	v_mul_f32_e32 v94, v69, v90
	s_waitcnt lgkmcnt(1)
	v_fmac_f32_e32 v78, v94, v82
	v_and_b32_e32 v82, 0xffff0000, v30
	v_mul_f32_e32 v82, v68, v82
	v_mul_f32_e32 v79, v82, v79
	v_and_b32_e32 v82, 0xffff0000, v32
	v_mul_f32_e32 v82, v69, v82
	v_fmac_f32_e32 v79, v82, v83
	v_lshlrev_b32_e32 v82, 16, v31
	v_mul_f32_e32 v82, v68, v82
	v_mul_f32_e32 v80, v82, v80
	v_lshlrev_b32_e32 v82, 16, v33
	v_mul_f32_e32 v82, v69, v82
	v_fmac_f32_e32 v80, v82, v84
	v_and_b32_e32 v82, 0xffff0000, v31
	v_mul_f32_e32 v82, v68, v82
	v_mul_f32_e32 v81, v82, v81
	v_and_b32_e32 v82, 0xffff0000, v33
	v_mul_f32_e32 v79, v79, v79
	ds_read_b128 v[90:93], v71 offset:9216
	v_mul_f32_e32 v82, v69, v82
	v_fmac_f32_e32 v79, v78, v78
	v_fmac_f32_e32 v81, v82, v85
	v_fmac_f32_e32 v79, v80, v80
	v_fmac_f32_e32 v79, v81, v81
	v_add_f32_e32 v77, v77, v79
	v_lshlrev_b32_e32 v79, 16, v28
	v_lshlrev_b32_e32 v78, 16, v26
	v_mul_f32_e32 v79, v69, v79
	v_mul_f32_e32 v78, v68, v78
	s_waitcnt lgkmcnt(0)
	v_mul_f32_e32 v79, v79, v90
	v_and_b32_e32 v80, 0xffff0000, v28
	v_fmac_f32_e32 v79, v78, v86
	v_and_b32_e32 v78, 0xffff0000, v26
	v_mul_f32_e32 v80, v69, v80
	v_mul_f32_e32 v78, v68, v78
	v_mul_f32_e32 v80, v80, v91
	v_lshlrev_b32_e32 v81, 16, v29
	v_fmac_f32_e32 v80, v78, v87
	v_lshlrev_b32_e32 v78, 16, v27
	v_mul_f32_e32 v81, v69, v81
	v_mul_f32_e32 v78, v68, v78
	v_mul_f32_e32 v81, v81, v92
	v_and_b32_e32 v82, 0xffff0000, v29
	v_fmac_f32_e32 v81, v78, v88
	v_and_b32_e32 v78, 0xffff0000, v27
	v_mul_f32_e32 v82, v69, v82
	v_mul_f32_e32 v78, v68, v78
	v_mul_f32_e32 v82, v82, v93
	v_fmac_f32_e32 v82, v78, v89
	v_mul_f32_e32 v78, v80, v80
	v_fmac_f32_e32 v78, v79, v79
	v_fmac_f32_e32 v78, v81, v81
	v_fmac_f32_e32 v78, v82, v82
	v_add_f32_e32 v77, v77, v78
	ds_read_b128 v[78:81], v71 offset:43008
	ds_read_b128 v[82:85], v71 offset:10240
	v_lshlrev_b32_e32 v90, 16, v22
	v_mul_f32_e32 v90, v68, v90
	ds_read_b128 v[86:89], v71 offset:44032
	s_waitcnt lgkmcnt(2)
; #define LAS __attribute__((address_space(3)))
; __device__ __forceinline__ float bflo(unsigned w) { return __uint_as_float(w << 16); }
; __device__ __forceinline__ float bfhi(unsigned w) { return __uint_as_float(w & 0xffff0000u); }
; template <int MODE> ...
;     ...
;             for (int j = 0; j < 16; ++j) { const f32x4 g = *(const LAS f32x4*)(GP + lo4 + 256 * j), gi = *(const LAS f32x4*)(GI + lo4 + 256 * j);
;                 f32x4 x;
;                 x.x = bflo(pw[j].x) * ri * gi.x + bflo(hw[j].x) * rstd * g.x; x.y = bfhi(pw[j].x) * ri * gi.y + bfhi(hw[j].x) * rstd * g.y;
;                 x.z = bflo(pw[j].y) * ri * gi.z + bflo(hw[j].y) * rstd * g.z; x.w = bfhi(pw[j].y) * ri * gi.w + bfhi(hw[j].y) * rstd * g.w;
;                 if (MODE == 2) *(f32x4*)(xout + (size_t)row * DM + lo4 + 256 * j) = x;
;                 else ss2 += x.x * x.x + x.y * x.y + x.z * x.z + x.w * x.w;
;                 if (j & 1) __builtin_amdgcn_sched_barrier(0); }
;             if (MODE == 1) {
;                 const float rstd2 = rsqrtf(wave_sum(ss2) * (1.f / DM) + EPS);
;                 if (lane == 0) rs_out[row] = rstd2;
	v_mul_f32_e32 v78, v90, v78
	v_lshlrev_b32_e32 v90, 16, v24
	v_mul_f32_e32 v94, v69, v90
	s_waitcnt lgkmcnt(1)
	v_fmac_f32_e32 v78, v94, v82
	v_and_b32_e32 v82, 0xffff0000, v22
	v_mul_f32_e32 v82, v68, v82
	v_mul_f32_e32 v79, v82, v79
	v_and_b32_e32 v82, 0xffff0000, v24
	v_mul_f32_e32 v82, v69, v82
	v_fmac_f32_e32 v79, v82, v83
	v_lshlrev_b32_e32 v82, 16, v23
	v_mul_f32_e32 v82, v68, v82
	v_mul_f32_e32 v80, v82, v80
	v_lshlrev_b32_e32 v82, 16, v25
	v_mul_f32_e32 v82, v69, v82
	v_fmac_f32_e32 v80, v82, v84
	v_and_b32_e32 v82, 0xffff0000, v23
	v_mul_f32_e32 v82, v68, v82
	v_mul_f32_e32 v81, v82, v81
	v_and_b32_e32 v82, 0xffff0000, v25
	v_mul_f32_e32 v79, v79, v79
	ds_read_b128 v[90:93], v71 offset:11264
	v_mul_f32_e32 v82, v69, v82
	v_fmac_f32_e32 v79, v78, v78
	v_fmac_f32_e32 v81, v82, v85
	v_fmac_f32_e32 v79, v80, v80
	v_fmac_f32_e32 v79, v81, v81
	v_add_f32_e32 v77, v77, v79
	v_lshlrev_b32_e32 v79, 16, v20
	v_lshlrev_b32_e32 v78, 16, v18
	v_mul_f32_e32 v79, v69, v79
	v_mul_f32_e32 v78, v68, v78
	s_waitcnt lgkmcnt(0)
	v_mul_f32_e32 v79, v79, v90
	v_and_b32_e32 v80, 0xffff0000, v20
	v_fmac_f32_e32 v79, v78, v86
	v_and_b32_e32 v78, 0xffff0000, v18
	v_mul_f32_e32 v80, v69, v80
	v_mul_f32_e32 v78, v68, v78
	v_mul_f32_e32 v80, v80, v91
	v_lshlrev_b32_e32 v81, 16, v21
	v_fmac_f32_e32 v80, v78, v87
	v_lshlrev_b32_e32 v78, 16, v19
	v_mul_f32_e32 v81, v69, v81
	v_mul_f32_e32 v78, v68, v78
	v_mul_f32_e32 v81, v81, v92
	v_and_b32_e32 v82, 0xffff0000, v21
	v_fmac_f32_e32 v81, v78, v88
	v_and_b32_e32 v78, 0xffff0000, v19
	v_mul_f32_e32 v82, v69, v82
	v_mul_f32_e32 v78, v68, v78
	v_mul_f32_e32 v82, v82, v93
	v_fmac_f32_e32 v82, v78, v89
	v_mul_f32_e32 v78, v80, v80
	v_fmac_f32_e32 v78, v79, v79
	v_fmac_f32_e32 v78, v81, v81
	v_fmac_f32_e32 v78, v82, v82
	v_add_f32_e32 v77, v77, v78
	ds_read_b128 v[78:81], v71 offset:45056
	ds_read_b128 v[82:85], v71 offset:46080
	ds_read_b128 v[86:89], v71 offset:12288
	ds_read_b128 v[90:93], v71 offset:13312
	v_lshlrev_b32_e32 v103, 16, v14
	v_lshlrev_b32_e32 v102, 16, v12
	v_lshlrev_b32_e32 v94, 16, v10
	v_lshlrev_b32_e32 v95, 16, v16
	v_pk_mul_f32 v[102:103], v[68:69], v[102:103] op_sel:[1,0] op_sel_hi:[0,1]
	s_waitcnt lgkmcnt(0)
	v_mov_b32_e32 v104, v90
	v_mov_b32_e32 v105, v78
	v_pk_mul_f32 v[94:95], v[68:69], v[94:95]
	v_mov_b32_e32 v96, v82
	v_mov_b32_e32 v97, v86
	v_pk_mul_f32 v[102:103], v[102:103], v[104:105]
	v_mov_b32_e32 v86, v83
	v_and_b32_e32 v83, 0xffff0000, v14
	v_and_b32_e32 v82, 0xffff0000, v12
	v_pk_fma_f32 v[94:95], v[94:95], v[96:97], v[102:103]
	v_and_b32_e32 v97, 0xffff0000, v16
	v_and_b32_e32 v96, 0xffff0000, v10
	v_pk_mul_f32 v[82:83], v[68:69], v[82:83] op_sel:[1,0] op_sel_hi:[0,1]
	v_mov_b32_e32 v78, v91
	v_pk_mul_f32 v[96:97], v[68:69], v[96:97]
	v_pk_mul_f32 v[78:79], v[82:83], v[78:79]
	v_lshlrev_b32_e32 v91, 16, v15
	v_lshlrev_b32_e32 v90, 16, v13
	v_pk_fma_f32 v[78:79], v[96:97], v[86:87], v[78:79]
	v_lshlrev_b32_e32 v82, 16, v11
	v_lshlrev_b32_e32 v83, 16, v17
	v_pk_mul_f32 v[90:91], v[68:69], v[90:91] op_sel:[1,0] op_sel_hi:[0,1]
	v_mov_b32_e32 v96, v92
	v_mov_b32_e32 v97, v80
	v_pk_mul_f32 v[82:83], v[68:69], v[82:83]
	v_mov_b32_e32 v86, v84
	v_mov_b32_e32 v87, v88
	v_pk_mul_f32 v[90:91], v[90:91], v[96:97]
	v_mov_b32_e32 v88, v85
	v_and_b32_e32 v85, 0xffff0000, v15
	v_and_b32_e32 v84, 0xffff0000, v13
	v_pk_fma_f32 v[82:83], v[82:83], v[86:87], v[90:91]
	v_and_b32_e32 v87, 0xffff0000, v17
	v_and_b32_e32 v86, 0xffff0000, v11
	v_pk_mul_f32 v[84:85], v[68:69], v[84:85] op_sel:[1,0] op_sel_hi:[0,1]
	v_mov_b32_e32 v80, v93
	v_pk_mul_f32 v[78:79], v[78:79], v[78:79]
	v_pk_mul_f32 v[86:87], v[68:69], v[86:87]
	v_pk_mul_f32 v[80:81], v[84:85], v[80:81]
	v_pk_fma_f32 v[78:79], v[94:95], v[94:95], v[78:79]
	v_pk_fma_f32 v[80:81], v[86:87], v[88:89], v[80:81]
	v_pk_fma_f32 v[78:79], v[82:83], v[82:83], v[78:79]
	s_nop 0
	v_pk_fma_f32 v[78:79], v[80:81], v[80:81], v[78:79]
	s_nop 0
	v_add_f32_e32 v77, v77, v79
	v_add_f32_e32 v77, v77, v78
	ds_read_b128 v[78:81], v71 offset:47104
	ds_read_b128 v[82:85], v71 offset:48128
	ds_read_b128 v[86:89], v71 offset:14336
	ds_read_b128 v[90:93], v71 offset:15360
	v_lshlrev_b32_e32 v103, 16, v6
	v_lshlrev_b32_e32 v102, 16, v4
	v_lshlrev_b32_e32 v94, 16, v2
	v_lshlrev_b32_e32 v95, 16, v8
	v_pk_mul_f32 v[102:103], v[68:69], v[102:103] op_sel:[1,0] op_sel_hi:[0,1]
	s_waitcnt lgkmcnt(0)
	v_mov_b32_e32 v104, v90
	v_mov_b32_e32 v105, v78
	v_pk_mul_f32 v[94:95], v[68:69], v[94:95]
	v_mov_b32_e32 v96, v82
	v_mov_b32_e32 v97, v86
	v_pk_mul_f32 v[102:103], v[102:103], v[104:105]
	v_mov_b32_e32 v86, v83
	v_and_b32_e32 v83, 0xffff0000, v6
	v_and_b32_e32 v82, 0xffff0000, v4
	v_pk_fma_f32 v[94:95], v[94:95], v[96:97], v[102:103]
	v_and_b32_e32 v97, 0xffff0000, v8
	v_and_b32_e32 v96, 0xffff0000, v2
	v_pk_mul_f32 v[82:83], v[68:69], v[82:83] op_sel:[1,0] op_sel_hi:[0,1]
	v_mov_b32_e32 v78, v91
	v_pk_mul_f32 v[96:97], v[68:69], v[96:97]
	v_pk_mul_f32 v[78:79], v[82:83], v[78:79]
	v_lshlrev_b32_e32 v91, 16, v7
	v_lshlrev_b32_e32 v90, 16, v5
	v_pk_fma_f32 v[78:79], v[96:97], v[86:87], v[78:79]
	v_lshlrev_b32_e32 v82, 16, v3
	v_lshlrev_b32_e32 v83, 16, v9
	v_pk_mul_f32 v[90:91], v[68:69], v[90:91] op_sel:[1,0] op_sel_hi:[0,1]
	v_mov_b32_e32 v96, v92
	v_mov_b32_e32 v97, v80
	v_pk_mul_f32 v[82:83], v[68:69], v[82:83]
	v_mov_b32_e32 v86, v84
	v_mov_b32_e32 v87, v88
	v_pk_mul_f32 v[90:91], v[90:91], v[96:97]
	v_mov_b32_e32 v88, v85
	v_and_b32_e32 v85, 0xffff0000, v7
	v_and_b32_e32 v84, 0xffff0000, v5
	v_pk_fma_f32 v[82:83], v[82:83], v[86:87], v[90:91]
	v_and_b32_e32 v87, 0xffff0000, v9
	v_and_b32_e32 v86, 0xffff0000, v3
	v_pk_mul_f32 v[84:85], v[68:69], v[84:85] op_sel:[1,0] op_sel_hi:[0,1]
	v_mov_b32_e32 v80, v93
	v_pk_mul_f32 v[78:79], v[78:79], v[78:79]
	v_pk_mul_f32 v[86:87], v[68:69], v[86:87]
	v_pk_mul_f32 v[80:81], v[84:85], v[80:81]
	v_pk_fma_f32 v[78:79], v[94:95], v[94:95], v[78:79]
	v_pk_fma_f32 v[80:81], v[86:87], v[88:89], v[80:81]
	v_pk_fma_f32 v[78:79], v[82:83], v[82:83], v[78:79]
	s_nop 0
	v_pk_fma_f32 v[78:79], v[80:81], v[80:81], v[78:79]
	s_nop 0
	v_add_f32_e32 v77, v77, v79
	v_add_f32_e32 v77, v77, v78
	ds_bpermute_b32 v70, v70, v77
	s_waitcnt lgkmcnt(0)
	v_add_f32_e32 v70, v77, v70
	ds_bpermute_b32 v72, v72, v70
	s_waitcnt lgkmcnt(0)
	v_add_f32_e32 v70, v70, v72
	ds_bpermute_b32 v72, v73, v70
	s_waitcnt lgkmcnt(0)
	v_add_f32_e32 v70, v70, v72
	ds_bpermute_b32 v72, v74, v70
	s_waitcnt lgkmcnt(0)
	v_add_f32_e32 v70, v70, v72
	ds_bpermute_b32 v72, v75, v70
	s_waitcnt lgkmcnt(0)
	v_add_f32_e32 v70, v70, v72
	ds_bpermute_b32 v72, v76, v70
	s_waitcnt lgkmcnt(0)
	v_add_f32_e32 v70, v70, v72
	v_fmamk_f32 v70, v70, 0x39800000, v99
	v_mul_f32_e32 v72, 0x4b800000, v70
	v_cmp_gt_f32_e32 vcc, s66, v70
	s_nop 1
	v_cndmask_b32_e32 v70, v70, v72, vcc
	v_rsq_f32_e32 v70, v70
	s_nop 0
	v_mul_f32_e32 v72, 0x45800000, v70
	v_cndmask_b32_e32 v70, v70, v72, vcc
	s_and_saveexec_b64 s[6:7], s[4:5]
	s_cbranch_execz .LBB0_775
	global_store_dword v98, v70, s[62:63]
	s_branch .LBB0_775

; #define LAS __attribute__((address_space(3)))
; template <int MODE> ...
;     ...
;     LAS float* GP = (LAS float*)lds; LAS float* GN = (LAS float*)(lds + 16384); LAS float* GI = (LAS float*)(lds + 32768);
;     __syncthreads();
; #pragma unroll
;     for (int i = 0; i < 2; ++i) { const int o = 4 * (tid + NTHREADS * i);
;         if (MODE != 0) { *(LAS f32x4*)(GP + o) = *(const f32x4*)(gpost + o); const f32x4 g = *(const f32x4*)(gprev + o); *(LAS f32x4*)(GI + o) = (f32x4){1.f / g.x, 1.f / g.y, 1.f / g.z, 1.f / g.w}; }
;         if (MODE != 2) *(LAS f32x4*)(GN + o) = *(const f32x4*)(gpre + o); }
;     __syncthreads();
.LBB0_1115:
	s_cmp_gt_i32 s36, 10
	s_cselect_b64 s[6:7], -1, 0
	s_xor_b64 s[4:5], s[4:5], -1
	s_or_b64 s[4:5], s[6:7], s[4:5]
	s_and_b64 vcc, exec, s[4:5]
	s_cbranch_vccnz .LBB0_1121
	s_mov_b64 s[12:13], 0
	s_waitcnt vmcnt(0)
	v_mbcnt_lo_u32_b32 v2, -1, 0
	v_mbcnt_hi_u32_b32 v2, -1, v2
	s_load_dwordx4 s[4:7], s[0:1], 0x70
	s_load_dwordx2 s[8:9], s[0:1], 0xa8
	v_lshlrev_b32_e32 v0, 2, v2
	v_lshl_add_u32 v24, s89, 8, v0
	v_ashrrev_i32_e32 v25, 31, v24
	v_lshlrev_b64 v[12:13], 2, v[24:25]
	v_add_u32_e32 v16, 0x800, v24
	s_waitcnt lgkmcnt(0)
	v_lshl_add_u64 v[8:9], s[4:5], 0, v[12:13]
	v_ashrrev_i32_e32 v17, 31, v16
	s_barrier
	v_lshl_add_u64 v[4:5], s[6:7], 0, v[12:13]
	global_load_dwordx4 v[8:11], v[8:9], off
	v_lshl_add_u64 v[12:13], s[8:9], 0, v[12:13]
	v_lshlrev_b64 v[26:27], 2, v[16:17]
	global_load_dwordx4 v[4:7], v[4:5], off
	v_lshl_add_u64 v[16:17], s[6:7], 0, v[26:27]
	global_load_dwordx4 v[12:15], v[12:13], off
	v_lshl_add_u64 v[20:21], s[4:5], 0, v[26:27]
	global_load_dwordx4 v[16:19], v[16:17], off
	v_lshl_add_u32 v1, v24, 2, 0
	global_load_dwordx4 v[20:23], v[20:21], off
	v_lshl_add_u64 v[24:25], s[8:9], 0, v[26:27]
	global_load_dwordx4 v[24:27], v[24:25], off
	s_cmpk_gt_i32 s40, 0x1fff
	s_waitcnt vmcnt(5)
	v_div_scale_f32 v3, s[4:5], v8, v8, 1.0
	v_div_scale_f32 v29, s[8:9], v11, v11, 1.0
	s_waitcnt vmcnt(4)
	ds_write_b128 v1, v[4:7]
	v_div_scale_f32 v5, s[4:5], v9, v9, 1.0
	s_waitcnt vmcnt(3)
	ds_write_b128 v1, v[12:15] offset:16384
	v_rcp_f32_e32 v12, v3
	v_div_scale_f32 v7, s[6:7], v10, v10, 1.0
	v_rcp_f32_e32 v13, v5
	s_waitcnt vmcnt(2)
	ds_write_b128 v1, v[16:19] offset:8192
	s_waitcnt vmcnt(1)
	v_div_scale_f32 v16, s[10:11], v20, v20, 1.0
	v_rcp_f32_e32 v14, v7
	v_rcp_f32_e32 v19, v16
	v_rcp_f32_e32 v15, v29
	v_fma_f32 v32, -v3, v12, 1.0
	v_div_scale_f32 v4, vcc, 1.0, v8, 1.0
	v_fma_f32 v33, -v5, v13, 1.0
	v_fmac_f32_e32 v12, v32, v12
	v_div_scale_f32 v6, s[4:5], 1.0, v9, 1.0
	v_fma_f32 v34, -v7, v14, 1.0
	v_fmac_f32_e32 v13, v33, v13
	v_fma_f32 v32, -v16, v19, 1.0
	v_mul_f32_e32 v33, v4, v12
	v_div_scale_f32 v28, s[6:7], 1.0, v10, 1.0
	v_fma_f32 v35, -v29, v15, 1.0
	v_fmac_f32_e32 v14, v34, v14
	v_mul_f32_e32 v34, v6, v13
	v_fmac_f32_e32 v19, v32, v19
	v_fma_f32 v32, -v3, v33, v4
	v_div_scale_f32 v30, s[8:9], 1.0, v11, 1.0
	v_fmac_f32_e32 v15, v35, v15
	v_mul_f32_e32 v35, v28, v14
	v_fma_f32 v37, -v5, v34, v6
	v_fmac_f32_e32 v33, v32, v12
	v_div_scale_f32 v17, s[10:11], 1.0, v20, 1.0
	v_mul_f32_e32 v36, v30, v15
	v_fma_f32 v38, -v7, v35, v28
	v_fmac_f32_e32 v34, v37, v13
	v_fma_f32 v3, -v3, v33, v4
	v_div_scale_f32 v18, s[14:15], v21, v21, 1.0
	v_fma_f32 v39, -v29, v36, v30
	v_mul_f32_e32 v40, v17, v19
	v_fmac_f32_e32 v35, v38, v14
	v_fma_f32 v5, -v5, v34, v6
	v_div_fmas_f32 v3, v3, v12, v33
	s_mov_b64 vcc, s[4:5]
	v_rcp_f32_e32 v31, v18
	v_fmac_f32_e32 v36, v39, v15
	v_fma_f32 v32, -v16, v40, v17
	v_fma_f32 v6, -v7, v35, v28
	v_div_fixup_f32 v4, v3, v8, 1.0
	v_div_fmas_f32 v3, v5, v13, v34
	s_mov_b64 vcc, s[6:7]
	v_fma_f32 v7, -v29, v36, v30
	v_fmac_f32_e32 v40, v32, v19
	v_div_fixup_f32 v5, v3, v9, 1.0
	v_div_fmas_f32 v3, v6, v14, v35
	s_mov_b64 vcc, s[8:9]
	v_fma_f32 v12, -v16, v40, v17
	v_div_fixup_f32 v6, v3, v10, 1.0
	v_div_fmas_f32 v3, v7, v15, v36
	s_mov_b64 vcc, s[10:11]
	v_div_fixup_f32 v7, v3, v11, 1.0
	v_div_fmas_f32 v3, v12, v19, v40
	ds_write_b128 v1, v[4:7] offset:32768
	v_div_fixup_f32 v4, v3, v20, 1.0
	v_fma_f32 v3, -v18, v31, 1.0
	v_fmac_f32_e32 v31, v3, v31
	v_div_scale_f32 v3, vcc, 1.0, v21, 1.0
	v_mul_f32_e32 v5, v3, v31
	v_fma_f32 v6, -v18, v5, v3
	v_fmac_f32_e32 v5, v6, v31
	v_div_scale_f32 v6, s[4:5], v22, v22, 1.0
	v_rcp_f32_e32 v7, v6
	v_fma_f32 v3, -v18, v5, v3
	v_div_fmas_f32 v3, v3, v31, v5
	v_div_fixup_f32 v5, v3, v21, 1.0
	v_fma_f32 v3, -v6, v7, 1.0
	v_fmac_f32_e32 v7, v3, v7
	v_div_scale_f32 v3, vcc, 1.0, v22, 1.0
	v_mul_f32_e32 v8, v3, v7
	v_fma_f32 v9, -v6, v8, v3
	v_fmac_f32_e32 v8, v9, v7
	v_div_scale_f32 v9, s[4:5], v23, v23, 1.0
	v_rcp_f32_e32 v10, v9
	v_fma_f32 v3, -v6, v8, v3
	v_div_fmas_f32 v3, v3, v7, v8
	v_div_fixup_f32 v6, v3, v22, 1.0
	v_fma_f32 v3, -v9, v10, 1.0
	v_fmac_f32_e32 v10, v3, v10
	v_div_scale_f32 v3, vcc, 1.0, v23, 1.0
	v_mul_f32_e32 v7, v3, v10
	v_fma_f32 v8, -v9, v7, v3
	v_fmac_f32_e32 v7, v8, v10
	v_fma_f32 v3, -v9, v7, v3
	v_div_fmas_f32 v3, v3, v10, v7
	v_div_fixup_f32 v7, v3, v23, 1.0
	ds_write_b128 v1, v[4:7] offset:40960
	s_waitcnt vmcnt(0)
	ds_write_b128 v1, v[24:27] offset:24576
	s_waitcnt lgkmcnt(0)
	s_barrier
; #define LAS __attribute__((address_space(3)))
; __device__ __forceinline__ unsigned pk2(float lo, float hi) { const f32x2c v = {lo, hi}; return __builtin_bit_cast(unsigned, __builtin_convertvector(v, bf16x2c)); }
; template <int MODE> ...
;     ...
;     const int lo4 = 4 * lane;
; #pragma unroll 1
;     for (int row = gw; row < SEQ; row += NGW) {
;         asm volatile("" ::: "memory");
;         if (MODE == 0) {
;             const float* xr = xin + (size_t)row * DM; bf16* nw = xn_out + (size_t)row * DM;
;             f32x4 xv[16]; float ss = 0.f;
; #pragma unroll
;             for (int j = 0; j < 16; ++j) { xv[j] = *(const f32x4*)(xr + lo4 + 256 * j); ss += xv[j].x * xv[j].x + xv[j].y * xv[j].y + xv[j].z * xv[j].z + xv[j].w * xv[j].w; }
;             const float rstd = rsqrtf(wave_sum(ss) * (1.f / DM) + EPS);
;             if (lane == 0) rs_out[row] = rstd;
;             asm volatile("" ::: "memory");
; #pragma unroll
;             for (int j = 0; j < 16; ++j) { const f32x4 g = *(const LAS f32x4*)(GN + lo4 + 256 * j);
;                 v2u w; w.x = pk2(xv[j].x * rstd * g.x, xv[j].y * rstd * g.y); w.y = pk2(xv[j].z * rstd * g.z, xv[j].w * rstd * g.w);
;                 *(v2u*)(nw + lo4 + 256 * j) = w; }
;         } else {
;             const bf16* pr = xn + (size_t)row * DM; bf16* pw_out = xn_out + (size_t)row * DM; const bf16* hr = hb + (size_t)row * DM;
;             v2u pw[16], hw[16]; float ss = 0.f;
; #pragma unroll
;             for (int j = 0; j < 16; ++j) { pw[j] = *(const v2u*)(pr + lo4 + 256 * j); hw[j] = *(const v2u*)(hr + lo4 + 256 * j); }
	s_cbranch_scc1 .LBB0_1121
	s_load_dwordx2 s[6:7], s[0:1], 0xe8
	s_ashr_i32 s41, s40, 31
	s_lshl_b64 s[8:9], s[40:41], 2
	v_ashrrev_i32_e32 v1, 31, v0
	v_cmp_eq_u32_e64 s[4:5], 0, v2
	s_waitcnt lgkmcnt(0)
	s_add_u32 s8, s6, s8
	s_addc_u32 s9, s7, s9
	s_add_u32 s64, s8, 0x2c0000
	s_addc_u32 s65, s9, 0
	s_ashr_i32 s39, s38, 31
	s_lshl_b64 s[8:9], s[38:39], 2
	s_lshl_b64 s[10:11], s[40:41], 13
	s_add_u32 s6, s6, s10
	s_addc_u32 s7, s7, s11
	v_mbcnt_lo_u32_b32 v2, -1, 0
	v_lshl_add_u32 v71, v0, 2, 0
	v_lshl_add_u64 v[0:1], v[0:1], 1, s[6:7]
	s_lshl_b64 s[10:11], s[38:39], 13
	s_mov_b64 s[14:15], 0x3000000
	s_mov_b64 s[18:19], 0x3000200
	s_mov_b64 s[20:21], 0x3000400
	s_mov_b64 s[22:23], 0x3000600
	s_mov_b64 s[24:25], 0x3000800
	s_mov_b64 s[26:27], 0x3000a00
	s_mov_b64 s[42:43], 0x3000c00
	s_mov_b64 s[44:45], 0x3000e00
	s_mov_b64 s[46:47], 0x3001000
	s_mov_b32 s39, 0x3001000
	s_mov_b32 s41, 0x7001000
	s_mov_b64 s[48:49], 0x3001200
	s_mov_b64 s[50:51], 0x3001400
	s_mov_b64 s[52:53], 0x3001600
	s_mov_b64 s[54:55], 0x3001800
	s_mov_b64 s[56:57], 0x3001a00
	s_mov_b64 s[58:59], 0x3001c00
	s_mov_b64 s[60:61], 0x3001e00
	v_mov_b32_e32 v79, 0
	v_mov_b32_e32 v100, 0x358637bd
	s_mov_b32 s66, 0x800000
	v_mbcnt_hi_u32_b32 v101, -1, v2
	s_mov_b32 s67, s40
	v_lshl_add_u64 v[214:215], v[0:1], 0, s[12:13]
	s_add_u32 s100, s64, s12
	s_addc_u32 s101, s65, s13
	v_add_co_u32_e32 v206, vcc, 0x3000000, v214
	s_nop 1
	v_addc_co_u32_e32 v207, vcc, 0, v215, vcc
	v_add_co_u32_e32 v208, vcc, 0x7000000, v214
	s_nop 1
	v_addc_co_u32_e32 v209, vcc, 0, v215, vcc
	v_add_co_u32_e32 v210, vcc, s39, v214
	s_nop 1
	v_addc_co_u32_e32 v211, vcc, 0, v215, vcc
	v_add_co_u32_e32 v212, vcc, s41, v214
	s_nop 1
	v_addc_co_u32_e32 v213, vcc, 0, v215, vcc
	global_load_dwordx2 v[198:199], v[208:209], off
	global_load_dwordx2 v[194:195], v[208:209], off offset:512
	global_load_dwordx2 v[192:193], v[208:209], off offset:1024
	global_load_dwordx2 v[188:189], v[208:209], off offset:1536
	global_load_dwordx2 v[184:185], v[208:209], off offset:2048
	global_load_dwordx2 v[182:183], v[208:209], off offset:2560
	global_load_dwordx2 v[178:179], v[208:209], off offset:3072
	global_load_dwordx2 v[170:171], v[210:211], off
	global_load_dwordx2 v[166:167], v[210:211], off offset:512
	global_load_dwordx2 v[160:161], v[210:211], off offset:1024
	global_load_dwordx2 v[156:157], v[210:211], off offset:1536
	global_load_dwordx2 v[172:173], v[212:213], off
	global_load_dwordx2 v[168:169], v[212:213], off offset:512
	global_load_dwordx2 v[162:163], v[212:213], off offset:1024
	global_load_dwordx2 v[158:159], v[212:213], off offset:1536
	global_load_dwordx2 v[174:175], v[208:209], off offset:3584
	global_load_dwordx2 v[152:153], v[210:211], off offset:2048
	global_load_dwordx2 v[148:149], v[210:211], off offset:2560
	global_load_dwordx2 v[144:145], v[210:211], off offset:3072
	global_load_dwordx2 v[140:141], v[210:211], off offset:3584
	global_load_dwordx2 v[154:155], v[212:213], off offset:2048
	global_load_dwordx2 v[150:151], v[212:213], off offset:2560
	global_load_dwordx2 v[146:147], v[212:213], off offset:3072
	global_load_dwordx2 v[142:143], v[212:213], off offset:3584
	global_load_dword v216, v79, s[100:101]
	global_load_dwordx2 v[204:205], v[206:207], off
	global_load_dwordx2 v[202:203], v[206:207], off offset:512
	global_load_dwordx2 v[200:201], v[206:207], off offset:1024
	global_load_dwordx2 v[196:197], v[206:207], off offset:1536
	global_load_dwordx2 v[190:191], v[206:207], off offset:2048
	global_load_dwordx2 v[186:187], v[206:207], off offset:2560
	global_load_dwordx2 v[180:181], v[206:207], off offset:3072
	global_load_dwordx2 v[176:177], v[206:207], off offset:3584
	s_waitcnt vmcnt(0)
	s_branch .Lnpf_body_1

; template <int MODE> ...
;     ...
;             const bf16* pr = xn + (size_t)row * DM; bf16* pw_out = xn_out + (size_t)row * DM; const bf16* hr = hb + (size_t)row * DM;
;             v2u pw[16], hw[16]; float ss = 0.f;
; #pragma unroll
;             for (int j = 0; j < 16; ++j) { pw[j] = *(const v2u*)(pr + lo4 + 256 * j); hw[j] = *(const v2u*)(hr + lo4 + 256 * j); }
.Lnpf_body_1:
	v_mov_b32_e32 v2, v140
	v_mov_b32_e32 v3, v141
	v_mov_b32_e32 v4, v142
	v_mov_b32_e32 v5, v143
	v_mov_b32_e32 v6, v144
	v_mov_b32_e32 v7, v145
	v_mov_b32_e32 v8, v146
	v_mov_b32_e32 v9, v147
	v_mov_b32_e32 v10, v148
	v_mov_b32_e32 v11, v149
	v_mov_b32_e32 v12, v150
	v_mov_b32_e32 v13, v151
	v_mov_b32_e32 v14, v152
	v_mov_b32_e32 v15, v153
	v_mov_b32_e32 v16, v154
	v_mov_b32_e32 v17, v155
	v_mov_b32_e32 v18, v156
	v_mov_b32_e32 v19, v157
	v_mov_b32_e32 v20, v158
	v_mov_b32_e32 v21, v159
	v_mov_b32_e32 v22, v160
	v_mov_b32_e32 v23, v161
	v_mov_b32_e32 v24, v162
	v_mov_b32_e32 v25, v163
	v_mov_b32_e32 v28, v166
	v_mov_b32_e32 v29, v167
	v_mov_b32_e32 v30, v168
	v_mov_b32_e32 v31, v169
	v_mov_b32_e32 v32, v170
	v_mov_b32_e32 v33, v171
	v_mov_b32_e32 v34, v172
	v_mov_b32_e32 v35, v173
	v_mov_b32_e32 v36, v174
	v_mov_b32_e32 v37, v175
	v_mov_b32_e32 v38, v176
	v_mov_b32_e32 v39, v177
	v_mov_b32_e32 v40, v178
	v_mov_b32_e32 v41, v179
	v_mov_b32_e32 v42, v180
	v_mov_b32_e32 v43, v181
	v_mov_b32_e32 v44, v182
	v_mov_b32_e32 v45, v183
	v_mov_b32_e32 v46, v184
	v_mov_b32_e32 v47, v185
	v_mov_b32_e32 v48, v186
	v_mov_b32_e32 v49, v187
	v_mov_b32_e32 v50, v188
	v_mov_b32_e32 v51, v189
	v_mov_b32_e32 v52, v190
	v_mov_b32_e32 v53, v191
	v_mov_b32_e32 v54, v192
	v_mov_b32_e32 v55, v193
	v_mov_b32_e32 v56, v194
	v_mov_b32_e32 v57, v195
	v_mov_b32_e32 v58, v196
	v_mov_b32_e32 v59, v197
	v_mov_b32_e32 v60, v198
	v_mov_b32_e32 v61, v199
	v_mov_b32_e32 v62, v200
	v_mov_b32_e32 v63, v201
	v_mov_b32_e32 v64, v202
	v_mov_b32_e32 v65, v203
	v_mov_b32_e32 v66, v204
	v_mov_b32_e32 v67, v205
	v_mov_b32_e32 v78, v216
	s_add_i32 s98, s67, s38
	s_cmpk_lt_i32 s98, 0x2000
	s_cbranch_scc0 .Lnpf_skip_1
	v_lshl_add_u64 v[214:215], v[0:1], 0, s[10:11]
	v_lshl_add_u64 v[214:215], v[214:215], 0, s[12:13]
	s_add_u32 s100, s64, s8
	s_addc_u32 s101, s65, s9
	s_add_u32 s100, s100, s12
	s_addc_u32 s101, s101, s13
	v_add_co_u32_e32 v206, vcc, 0x3000000, v214
	s_nop 1
	v_addc_co_u32_e32 v207, vcc, 0, v215, vcc
	v_add_co_u32_e32 v208, vcc, 0x7000000, v214
	s_nop 1
	v_addc_co_u32_e32 v209, vcc, 0, v215, vcc
	v_add_co_u32_e32 v210, vcc, s39, v214
	s_nop 1
	v_addc_co_u32_e32 v211, vcc, 0, v215, vcc
	v_add_co_u32_e32 v212, vcc, s41, v214
	s_nop 1
	v_addc_co_u32_e32 v213, vcc, 0, v215, vcc
	global_load_dwordx2 v[198:199], v[208:209], off
	global_load_dwordx2 v[194:195], v[208:209], off offset:512
	global_load_dwordx2 v[192:193], v[208:209], off offset:1024
	global_load_dwordx2 v[188:189], v[208:209], off offset:1536
	global_load_dwordx2 v[184:185], v[208:209], off offset:2048
	global_load_dwordx2 v[182:183], v[208:209], off offset:2560
	global_load_dwordx2 v[178:179], v[208:209], off offset:3072
	global_load_dwordx2 v[170:171], v[210:211], off
	global_load_dwordx2 v[166:167], v[210:211], off offset:512
	global_load_dwordx2 v[160:161], v[210:211], off offset:1024
	global_load_dwordx2 v[156:157], v[210:211], off offset:1536
	global_load_dwordx2 v[172:173], v[212:213], off
	global_load_dwordx2 v[168:169], v[212:213], off offset:512
	global_load_dwordx2 v[162:163], v[212:213], off offset:1024
	global_load_dwordx2 v[158:159], v[212:213], off offset:1536
	global_load_dwordx2 v[174:175], v[208:209], off offset:3584
	global_load_dwordx2 v[152:153], v[210:211], off offset:2048
	global_load_dwordx2 v[148:149], v[210:211], off offset:2560
	global_load_dwordx2 v[144:145], v[210:211], off offset:3072
	global_load_dwordx2 v[140:141], v[210:211], off offset:3584
	global_load_dwordx2 v[154:155], v[212:213], off offset:2048
	global_load_dwordx2 v[150:151], v[212:213], off offset:2560
	global_load_dwordx2 v[146:147], v[212:213], off offset:3072
	global_load_dwordx2 v[142:143], v[212:213], off offset:3584
	global_load_dword v216, v79, s[100:101]
	global_load_dwordx2 v[204:205], v[206:207], off
	global_load_dwordx2 v[202:203], v[206:207], off offset:512
	global_load_dwordx2 v[200:201], v[206:207], off offset:1024
	global_load_dwordx2 v[196:197], v[206:207], off offset:1536
	global_load_dwordx2 v[190:191], v[206:207], off offset:2048
	global_load_dwordx2 v[186:187], v[206:207], off offset:2560
	global_load_dwordx2 v[180:181], v[206:207], off offset:3072
	global_load_dwordx2 v[176:177], v[206:207], off offset:3584
; __device__ __forceinline__ float bflo(unsigned w) { return __uint_as_float(w << 16); }
; __device__ __forceinline__ float bfhi(unsigned w) { return __uint_as_float(w & 0xffff0000u); }
; template <int MODE> ...
;     ...
;             const bf16* pr = xn + (size_t)row * DM; bf16* pw_out = xn_out + (size_t)row * DM; const bf16* hr = hb + (size_t)row * DM;
;             v2u pw[16], hw[16]; float ss = 0.f;
; #pragma unroll
;             for (int j = 0; j < 16; ++j) { pw[j] = *(const v2u*)(pr + lo4 + 256 * j); hw[j] = *(const v2u*)(hr + lo4 + 256 * j); }
;             const float ri = 1.f / rs[row];
; #pragma unroll
;             for (int j = 0; j < 16; ++j) { const float a = bflo(hw[j].x), b = bfhi(hw[j].x), c = bflo(hw[j].y), d = bfhi(hw[j].y); ss += a * a + b * b + c * c + d * d; }
;             const float rstd = rsqrtf(wave_sum(ss) * (1.f / DM) + EPS);
.Lnpf_skip_1:
	v_lshl_add_u64 v[68:69], v[0:1], 0, s[12:13]
	s_add_u32 s62, s64, s12
	s_addc_u32 s63, s65, s13
	v_lshlrev_b32_e32 v70, 16, v61
	v_and_b32_e32 v27, 0xffff0000, v60
	v_and_b32_e32 v74, 0xffff0000, v56
	v_lshlrev_b32_e32 v26, 16, v60
	v_lshlrev_b32_e32 v73, 16, v56
	v_mul_f32_e32 v27, v27, v27
	v_mul_f32_e32 v74, v74, v74
	v_lshlrev_b32_e32 v75, 16, v57
	v_and_b32_e32 v80, 0xffff0000, v54
	v_fmac_f32_e32 v27, v26, v26
	v_fmac_f32_e32 v74, v73, v73
	v_and_b32_e32 v72, 0xffff0000, v61
	v_and_b32_e32 v76, 0xffff0000, v57
	v_lshlrev_b32_e32 v77, 16, v54
	v_and_b32_e32 v84, 0xffff0000, v50
	v_and_b32_e32 v88, 0xffff0000, v46
	v_mul_f32_e32 v80, v80, v80
	v_fmac_f32_e32 v27, v70, v70
	v_fmac_f32_e32 v74, v75, v75
	v_lshlrev_b32_e32 v81, 16, v55
	v_lshlrev_b32_e32 v83, 16, v50
	v_lshlrev_b32_e32 v87, 16, v46
	v_mul_f32_e32 v84, v84, v84
	v_fmac_f32_e32 v80, v77, v77
	v_fmac_f32_e32 v27, v72, v72
	v_fmac_f32_e32 v74, v76, v76
	v_mul_f32_e32 v72, v88, v88
	v_and_b32_e32 v82, 0xffff0000, v55
	v_lshlrev_b32_e32 v85, 16, v51
	v_fmac_f32_e32 v84, v83, v83
	v_fmac_f32_e32 v80, v81, v81
	v_add_f32_e32 v26, v27, v74
	v_lshlrev_b32_e32 v27, 16, v47
	v_fmac_f32_e32 v72, v87, v87
	v_and_b32_e32 v86, 0xffff0000, v51
	v_fmac_f32_e32 v84, v85, v85
	v_fmac_f32_e32 v80, v82, v82
	v_and_b32_e32 v70, 0xffff0000, v47
	v_fmac_f32_e32 v72, v27, v27
	v_fmac_f32_e32 v84, v86, v86
	v_add_f32_e32 v26, v26, v80
	v_fmac_f32_e32 v72, v70, v70
	v_and_b32_e32 v70, 0xffff0000, v44
	v_add_f32_e32 v26, v26, v84
	v_lshlrev_b32_e32 v27, 16, v44
	v_mul_f32_e32 v70, v70, v70
	v_add_f32_e32 v26, v26, v72
	v_lshlrev_b32_e32 v72, 16, v45
	v_fmac_f32_e32 v70, v27, v27
	v_and_b32_e32 v73, 0xffff0000, v45
	v_fmac_f32_e32 v70, v72, v72
	v_fmac_f32_e32 v70, v73, v73
	v_add_f32_e32 v26, v26, v70
	v_and_b32_e32 v70, 0xffff0000, v40
	v_lshlrev_b32_e32 v27, 16, v40
	v_mul_f32_e32 v70, v70, v70
	v_lshlrev_b32_e32 v72, 16, v41
	v_fmac_f32_e32 v70, v27, v27
	v_and_b32_e32 v73, 0xffff0000, v41
	v_fmac_f32_e32 v70, v72, v72
	v_fmac_f32_e32 v70, v73, v73
	v_add_f32_e32 v26, v26, v70
	v_and_b32_e32 v70, 0xffff0000, v36
	v_lshlrev_b32_e32 v27, 16, v36
	v_mul_f32_e32 v70, v70, v70
	v_lshlrev_b32_e32 v72, 16, v37
	v_fmac_f32_e32 v70, v27, v27
	v_and_b32_e32 v73, 0xffff0000, v37
	v_fmac_f32_e32 v70, v72, v72
	v_fmac_f32_e32 v70, v73, v73
	v_add_f32_e32 v26, v26, v70
	v_and_b32_e32 v70, 0xffff0000, v34
	v_lshlrev_b32_e32 v27, 16, v34
	v_mul_f32_e32 v70, v70, v70
	v_lshlrev_b32_e32 v72, 16, v35
	v_fmac_f32_e32 v70, v27, v27
	v_and_b32_e32 v73, 0xffff0000, v35
	v_fmac_f32_e32 v70, v72, v72
	v_fmac_f32_e32 v70, v73, v73
	v_add_f32_e32 v26, v26, v70
	v_and_b32_e32 v70, 0xffff0000, v30
	v_lshlrev_b32_e32 v27, 16, v30
	v_mul_f32_e32 v70, v70, v70
	v_lshlrev_b32_e32 v72, 16, v31
	v_fmac_f32_e32 v70, v27, v27
	v_and_b32_e32 v73, 0xffff0000, v31
	v_fmac_f32_e32 v70, v72, v72
	v_fmac_f32_e32 v70, v73, v73
	v_add_f32_e32 v26, v26, v70
	v_and_b32_e32 v70, 0xffff0000, v24
	v_lshlrev_b32_e32 v27, 16, v24
	v_mul_f32_e32 v70, v70, v70
	v_lshlrev_b32_e32 v72, 16, v25
	v_fmac_f32_e32 v70, v27, v27
	v_and_b32_e32 v73, 0xffff0000, v25
	v_fmac_f32_e32 v70, v72, v72
	v_fmac_f32_e32 v70, v73, v73
	v_add_f32_e32 v26, v26, v70
	v_and_b32_e32 v70, 0xffff0000, v20
	v_lshlrev_b32_e32 v27, 16, v20
	v_mul_f32_e32 v70, v70, v70
	v_lshlrev_b32_e32 v72, 16, v21
	v_fmac_f32_e32 v70, v27, v27
	v_and_b32_e32 v73, 0xffff0000, v21
	v_fmac_f32_e32 v70, v72, v72
	v_fmac_f32_e32 v70, v73, v73
	v_and_b32_e32 v73, 0xffff0000, v12
	v_and_b32_e32 v72, 0xffff0000, v16
	v_add_f32_e32 v70, v26, v70
	v_lshlrev_b32_e32 v27, 16, v12
	v_lshlrev_b32_e32 v26, 16, v16
	v_pk_mul_f32 v[72:73], v[72:73], v[72:73]
	v_lshlrev_b32_e32 v75, 16, v13
	v_lshlrev_b32_e32 v74, 16, v17
	v_pk_fma_f32 v[26:27], v[26:27], v[26:27], v[72:73]
	v_and_b32_e32 v77, 0xffff0000, v13
	v_and_b32_e32 v76, 0xffff0000, v17
	v_pk_fma_f32 v[26:27], v[74:75], v[74:75], v[26:27]
	v_and_b32_e32 v73, 0xffff0000, v4
	v_pk_fma_f32 v[26:27], v[76:77], v[76:77], v[26:27]
	v_and_b32_e32 v72, 0xffff0000, v8
	v_add_f32_e32 v26, v70, v26
	v_add_f32_e32 v70, v26, v27
	v_lshlrev_b32_e32 v27, 16, v4
	v_lshlrev_b32_e32 v26, 16, v8
	v_pk_mul_f32 v[72:73], v[72:73], v[72:73]
	v_lshlrev_b32_e32 v75, 16, v5
	v_lshlrev_b32_e32 v74, 16, v9
	v_pk_fma_f32 v[26:27], v[26:27], v[26:27], v[72:73]
	v_and_b32_e32 v77, 0xffff0000, v5
	v_and_b32_e32 v76, 0xffff0000, v9
	v_pk_fma_f32 v[26:27], v[74:75], v[74:75], v[26:27]
	v_pk_fma_f32 v[26:27], v[76:77], v[76:77], v[26:27]
	v_div_scale_f32 v77, s[6:7], v78, v78, 1.0
	v_add_f32_e32 v26, v70, v26
	v_add_f32_e32 v26, v26, v27
	v_and_b32_e32 v27, 64, v101
	v_add_u32_e32 v27, 64, v27
	v_xor_b32_e32 v70, 1, v101
	v_cmp_lt_i32_e32 vcc, v70, v27
	v_rcp_f32_e32 v80, v77
	s_nop 0
	v_cndmask_b32_e32 v70, v101, v70, vcc
	v_lshlrev_b32_e32 v70, 2, v70
	ds_bpermute_b32 v72, v70, v26
	v_fma_f32 v81, -v77, v80, 1.0
	v_fmac_f32_e32 v80, v81, v80
	s_waitcnt lgkmcnt(0)
	v_add_f32_e32 v26, v26, v72
	v_xor_b32_e32 v72, 2, v101
	v_cmp_lt_i32_e32 vcc, v72, v27
	s_nop 1
	v_cndmask_b32_e32 v72, v101, v72, vcc
	v_lshlrev_b32_e32 v72, 2, v72
	ds_bpermute_b32 v73, v72, v26
	s_waitcnt lgkmcnt(0)
	v_add_f32_e32 v26, v26, v73
	v_xor_b32_e32 v73, 4, v101
	v_cmp_lt_i32_e32 vcc, v73, v27
	s_nop 1
	v_cndmask_b32_e32 v73, v101, v73, vcc
	v_lshlrev_b32_e32 v73, 2, v73
	ds_bpermute_b32 v74, v73, v26
	s_waitcnt lgkmcnt(0)
	v_add_f32_e32 v26, v26, v74
	v_xor_b32_e32 v74, 8, v101
	v_cmp_lt_i32_e32 vcc, v74, v27
	s_nop 1
	v_cndmask_b32_e32 v74, v101, v74, vcc
	v_lshlrev_b32_e32 v74, 2, v74
	ds_bpermute_b32 v75, v74, v26
	s_waitcnt lgkmcnt(0)
; #define LAS __attribute__((address_space(3)))
; __device__ __forceinline__ float bflo(unsigned w) { return __uint_as_float(w << 16); }
; __device__ __forceinline__ float bfhi(unsigned w) { return __uint_as_float(w & 0xffff0000u); }
; #define LAUNDER_ROW(pw, hw) do { LAUNDER8(pw, 0); LAUNDER8(pw, 8); LAUNDER8(hw, 0); LAUNDER8(hw, 8); } while (0)
; template <int MODE> ...
;     ...
;             const float ri = 1.f / rs[row];
; #pragma unroll
;             for (int j = 0; j < 16; ++j) { const float a = bflo(hw[j].x), b = bfhi(hw[j].x), c = bflo(hw[j].y), d = bfhi(hw[j].y); ss += a * a + b * b + c * c + d * d; }
;             const float rstd = rsqrtf(wave_sum(ss) * (1.f / DM) + EPS);
;             asm volatile("" ::: "memory");
;             LAUNDER_ROW(pw, hw);
;             float ss2 = 0.f;
; #pragma unroll
;             for (int j = 0; j < 16; ++j) { const f32x4 g = *(const LAS f32x4*)(GP + lo4 + 256 * j), gi = *(const LAS f32x4*)(GI + lo4 + 256 * j);
;                 f32x4 x;
;                 x.x = bflo(pw[j].x) * ri * gi.x + bflo(hw[j].x) * rstd * g.x; x.y = bfhi(pw[j].x) * ri * gi.y + bfhi(hw[j].x) * rstd * g.y;
;                 x.z = bflo(pw[j].y) * ri * gi.z + bflo(hw[j].y) * rstd * g.z; x.w = bfhi(pw[j].y) * ri * gi.w + bfhi(hw[j].y) * rstd * g.w;
	v_add_f32_e32 v26, v26, v75
	v_xor_b32_e32 v75, 16, v101
	v_cmp_lt_i32_e32 vcc, v75, v27
	s_nop 1
	v_cndmask_b32_e32 v75, v101, v75, vcc
	v_lshlrev_b32_e32 v75, 2, v75
	ds_bpermute_b32 v76, v75, v26
	v_div_scale_f32 v81, vcc, 1.0, v78, 1.0
	v_mul_f32_e32 v82, v81, v80
	v_fma_f32 v83, -v77, v82, v81
	s_waitcnt lgkmcnt(0)
	v_add_f32_e32 v26, v26, v76
	v_xor_b32_e32 v76, 32, v101
	v_cmp_lt_i32_e64 s[6:7], v76, v27
	v_fmac_f32_e32 v82, v83, v80
	v_fma_f32 v77, -v77, v82, v81
	v_cndmask_b32_e64 v27, v101, v76, s[6:7]
	v_lshlrev_b32_e32 v76, 2, v27
	ds_bpermute_b32 v27, v76, v26
	s_waitcnt lgkmcnt(0)
	v_add_f32_e32 v26, v26, v27
	v_fmamk_f32 v26, v26, 0x39800000, v100
	v_mul_f32_e32 v27, 0x4b800000, v26
	v_cmp_gt_f32_e64 s[6:7], s66, v26
	s_nop 1
	v_cndmask_b32_e64 v26, v26, v27, s[6:7]
	v_rsq_f32_e32 v27, v26
	v_div_fmas_f32 v26, v77, v80, v82
	ds_read_b128 v[80:83], v71
	ds_read_b128 v[84:87], v71 offset:32768
	v_div_fixup_f32 v26, v26, v78, 1.0
	v_mul_f32_e32 v77, 0x45800000, v27
	v_cndmask_b32_e64 v27, v27, v77, s[6:7]
	v_lshlrev_b32_e32 v78, 16, v60
	v_lshlrev_b32_e32 v77, 16, v66
	v_mul_f32_e32 v78, v27, v78
	v_mul_f32_e32 v77, v26, v77
	s_waitcnt lgkmcnt(1)
	v_mul_f32_e32 v78, v80, v78
	v_and_b32_e32 v80, 0xffff0000, v60
	s_waitcnt lgkmcnt(0)
	v_fmac_f32_e32 v78, v77, v84
	v_and_b32_e32 v77, 0xffff0000, v66
	v_mul_f32_e32 v80, v27, v80
	v_mul_f32_e32 v77, v26, v77
	v_mul_f32_e32 v80, v81, v80
	v_lshlrev_b32_e32 v81, 16, v61
	v_fmac_f32_e32 v80, v77, v85
	v_lshlrev_b32_e32 v77, 16, v67
	v_mul_f32_e32 v81, v27, v81
	ds_read_b128 v[88:91], v71 offset:1024
	ds_read_b128 v[92:95], v71 offset:33792
	v_mul_f32_e32 v77, v26, v77
	v_mul_f32_e32 v81, v82, v81
	v_and_b32_e32 v82, 0xffff0000, v61
	v_fmac_f32_e32 v81, v77, v86
	v_and_b32_e32 v77, 0xffff0000, v67
	v_mul_f32_e32 v82, v27, v82
	v_mul_f32_e32 v77, v26, v77
	v_mul_f32_e32 v82, v83, v82
	v_fmac_f32_e32 v82, v77, v87
	v_mul_f32_e32 v77, v80, v80
	v_lshlrev_b32_e32 v80, 16, v56
	v_fmac_f32_e32 v77, v78, v78
	v_lshlrev_b32_e32 v78, 16, v64
	v_mul_f32_e32 v80, v27, v80
	v_fmac_f32_e32 v77, v81, v81
	v_mul_f32_e32 v78, v26, v78
	s_waitcnt lgkmcnt(1)
	v_mul_f32_e32 v80, v88, v80
	v_and_b32_e32 v81, 0xffff0000, v56
	s_waitcnt lgkmcnt(0)
	v_fmac_f32_e32 v80, v78, v92
	v_and_b32_e32 v78, 0xffff0000, v64
	v_mul_f32_e32 v81, v27, v81
	v_fmac_f32_e32 v77, v82, v82
	v_mul_f32_e32 v78, v26, v78
	v_mul_f32_e32 v81, v89, v81
	v_lshlrev_b32_e32 v82, 16, v57
	v_fmac_f32_e32 v81, v78, v93
	v_lshlrev_b32_e32 v78, 16, v65
	v_mul_f32_e32 v82, v27, v82
	v_mul_f32_e32 v78, v26, v78
	v_mul_f32_e32 v82, v90, v82
	v_and_b32_e32 v83, 0xffff0000, v57
	v_fmac_f32_e32 v82, v78, v94
	v_and_b32_e32 v78, 0xffff0000, v65
	v_mul_f32_e32 v83, v27, v83
	v_mul_f32_e32 v78, v26, v78
	v_mul_f32_e32 v83, v91, v83
	v_fmac_f32_e32 v83, v78, v95
	v_mul_f32_e32 v78, v81, v81
	v_fmac_f32_e32 v78, v80, v80
	v_fmac_f32_e32 v78, v82, v82
	v_fmac_f32_e32 v78, v83, v83
	v_add_f32_e32 v77, v77, v78
	ds_read_b128 v[80:83], v71 offset:34816
	ds_read_b128 v[84:87], v71 offset:2048
	v_lshlrev_b32_e32 v78, 16, v62
	v_mul_f32_e32 v78, v26, v78
	ds_read_b128 v[88:91], v71 offset:35840
	ds_read_b128 v[92:95], v71 offset:3072
	s_waitcnt lgkmcnt(3)
	v_mul_f32_e32 v78, v78, v80
	v_lshlrev_b32_e32 v80, 16, v54
	v_mul_f32_e32 v80, v27, v80
	s_waitcnt lgkmcnt(2)
	v_fmac_f32_e32 v78, v84, v80
	v_and_b32_e32 v80, 0xffff0000, v62
	v_mul_f32_e32 v80, v26, v80
	v_mul_f32_e32 v80, v80, v81
	v_and_b32_e32 v81, 0xffff0000, v54
	v_mul_f32_e32 v81, v27, v81
	v_fmac_f32_e32 v80, v85, v81
	v_lshlrev_b32_e32 v81, 16, v63
	v_mul_f32_e32 v81, v26, v81
	v_mul_f32_e32 v81, v81, v82
	v_lshlrev_b32_e32 v82, 16, v55
	v_mul_f32_e32 v82, v27, v82
	v_fmac_f32_e32 v81, v86, v82
	v_and_b32_e32 v82, 0xffff0000, v63
	v_mul_f32_e32 v82, v26, v82
	v_mul_f32_e32 v82, v82, v83
	v_and_b32_e32 v83, 0xffff0000, v55
	v_mul_f32_e32 v80, v80, v80
	v_mul_f32_e32 v83, v27, v83
	v_fmac_f32_e32 v80, v78, v78
	v_fmac_f32_e32 v82, v87, v83
	v_fmac_f32_e32 v80, v81, v81
	v_fmac_f32_e32 v80, v82, v82
	v_add_f32_e32 v77, v80, v77
	v_lshlrev_b32_e32 v80, 16, v50
	v_lshlrev_b32_e32 v78, 16, v58
	v_mul_f32_e32 v80, v27, v80
	v_mul_f32_e32 v78, v26, v78
	s_waitcnt lgkmcnt(0)
	v_mul_f32_e32 v80, v80, v92
	v_and_b32_e32 v81, 0xffff0000, v50
	v_fmac_f32_e32 v80, v78, v88
	v_and_b32_e32 v78, 0xffff0000, v58
	v_mul_f32_e32 v81, v27, v81
	v_mul_f32_e32 v78, v26, v78
	v_mul_f32_e32 v81, v81, v93
	v_lshlrev_b32_e32 v82, 16, v51
	v_fmac_f32_e32 v81, v78, v89
	v_lshlrev_b32_e32 v78, 16, v59
	v_mul_f32_e32 v82, v27, v82
	v_mul_f32_e32 v78, v26, v78
	v_mul_f32_e32 v82, v82, v94
	v_and_b32_e32 v83, 0xffff0000, v51
	v_fmac_f32_e32 v82, v78, v90
	v_and_b32_e32 v78, 0xffff0000, v59
	v_mul_f32_e32 v83, v27, v83
	v_mul_f32_e32 v78, v26, v78
	v_mul_f32_e32 v83, v83, v95
	v_fmac_f32_e32 v83, v78, v91
	v_mul_f32_e32 v78, v81, v81
	v_fmac_f32_e32 v78, v80, v80
	v_fmac_f32_e32 v78, v82, v82
	v_fmac_f32_e32 v78, v83, v83
	v_add_f32_e32 v77, v77, v78
	ds_read_b128 v[80:83], v71 offset:36864
	ds_read_b128 v[84:87], v71 offset:4096
	v_lshlrev_b32_e32 v78, 16, v52
	v_mul_f32_e32 v78, v26, v78
	ds_read_b128 v[88:91], v71 offset:37888
	ds_read_b128 v[92:95], v71 offset:5120
	s_waitcnt lgkmcnt(3)
	v_mul_f32_e32 v78, v78, v80
	v_lshlrev_b32_e32 v80, 16, v46
	v_mul_f32_e32 v80, v27, v80
	s_waitcnt lgkmcnt(2)
; #define LAS __attribute__((address_space(3)))
; __device__ __forceinline__ float bflo(unsigned w) { return __uint_as_float(w << 16); }
; __device__ __forceinline__ float bfhi(unsigned w) { return __uint_as_float(w & 0xffff0000u); }
; template <int MODE> ...
;     ...
;             for (int j = 0; j < 16; ++j) { const f32x4 g = *(const LAS f32x4*)(GP + lo4 + 256 * j), gi = *(const LAS f32x4*)(GI + lo4 + 256 * j);
;                 f32x4 x;
;                 x.x = bflo(pw[j].x) * ri * gi.x + bflo(hw[j].x) * rstd * g.x; x.y = bfhi(pw[j].x) * ri * gi.y + bfhi(hw[j].x) * rstd * g.y;
;                 x.z = bflo(pw[j].y) * ri * gi.z + bflo(hw[j].y) * rstd * g.z; x.w = bfhi(pw[j].y) * ri * gi.w + bfhi(hw[j].y) * rstd * g.w;
;                 if (MODE == 2) *(f32x4*)(xout + (size_t)row * DM + lo4 + 256 * j) = x;
;                 else ss2 += x.x * x.x + x.y * x.y + x.z * x.z + x.w * x.w;
;                 if (j & 1) __builtin_amdgcn_sched_barrier(0); }
	v_fmac_f32_e32 v78, v80, v84
	v_and_b32_e32 v80, 0xffff0000, v52
	v_mul_f32_e32 v80, v26, v80
	v_mul_f32_e32 v80, v80, v81
	v_and_b32_e32 v81, 0xffff0000, v46
	v_mul_f32_e32 v81, v27, v81
	v_fmac_f32_e32 v80, v81, v85
	v_lshlrev_b32_e32 v81, 16, v53
	v_mul_f32_e32 v81, v26, v81
	v_mul_f32_e32 v81, v81, v82
	v_lshlrev_b32_e32 v82, 16, v47
	v_mul_f32_e32 v82, v27, v82
	v_fmac_f32_e32 v81, v82, v86
	v_and_b32_e32 v82, 0xffff0000, v53
	v_mul_f32_e32 v82, v26, v82
	v_mul_f32_e32 v82, v82, v83
	v_and_b32_e32 v83, 0xffff0000, v47
	v_mul_f32_e32 v80, v80, v80
	v_mul_f32_e32 v83, v27, v83
	v_fmac_f32_e32 v80, v78, v78
	v_fmac_f32_e32 v82, v83, v87
	v_fmac_f32_e32 v80, v81, v81
	v_fmac_f32_e32 v80, v82, v82
	v_add_f32_e32 v77, v77, v80
	v_lshlrev_b32_e32 v80, 16, v44
	v_lshlrev_b32_e32 v78, 16, v48
	v_mul_f32_e32 v80, v27, v80
	v_mul_f32_e32 v78, v26, v78
	s_waitcnt lgkmcnt(0)
	v_mul_f32_e32 v80, v80, v92
	v_and_b32_e32 v81, 0xffff0000, v44
	v_fmac_f32_e32 v80, v78, v88
	v_and_b32_e32 v78, 0xffff0000, v48
	v_mul_f32_e32 v81, v27, v81
	v_mul_f32_e32 v78, v26, v78
	v_mul_f32_e32 v81, v81, v93
	v_lshlrev_b32_e32 v82, 16, v45
	v_fmac_f32_e32 v81, v78, v89
	v_lshlrev_b32_e32 v78, 16, v49
	v_mul_f32_e32 v82, v27, v82
	v_mul_f32_e32 v78, v26, v78
	v_mul_f32_e32 v82, v82, v94
	v_and_b32_e32 v83, 0xffff0000, v45
	v_fmac_f32_e32 v82, v78, v90
	v_and_b32_e32 v78, 0xffff0000, v49
	v_mul_f32_e32 v83, v27, v83
	v_mul_f32_e32 v78, v26, v78
	v_mul_f32_e32 v83, v83, v95
	v_fmac_f32_e32 v83, v78, v91
	v_mul_f32_e32 v78, v81, v81
	v_fmac_f32_e32 v78, v80, v80
	v_fmac_f32_e32 v78, v82, v82
	v_fmac_f32_e32 v78, v83, v83
	v_add_f32_e32 v77, v77, v78
	ds_read_b128 v[80:83], v71 offset:38912
	ds_read_b128 v[84:87], v71 offset:6144
	v_lshlrev_b32_e32 v78, 16, v42
	v_mul_f32_e32 v78, v26, v78
	ds_read_b128 v[88:91], v71 offset:39936
	ds_read_b128 v[92:95], v71 offset:7168
	s_waitcnt lgkmcnt(3)
	v_mul_f32_e32 v78, v78, v80
	v_lshlrev_b32_e32 v80, 16, v40
	v_mul_f32_e32 v80, v27, v80
	s_waitcnt lgkmcnt(2)
	v_fmac_f32_e32 v78, v80, v84
	v_and_b32_e32 v80, 0xffff0000, v42
	v_mul_f32_e32 v80, v26, v80
	v_mul_f32_e32 v80, v80, v81
	v_and_b32_e32 v81, 0xffff0000, v40
	v_mul_f32_e32 v81, v27, v81
	v_fmac_f32_e32 v80, v81, v85
	v_lshlrev_b32_e32 v81, 16, v43
	v_mul_f32_e32 v81, v26, v81
	v_mul_f32_e32 v81, v81, v82
	v_lshlrev_b32_e32 v82, 16, v41
	v_mul_f32_e32 v82, v27, v82
	v_fmac_f32_e32 v81, v82, v86
	v_and_b32_e32 v82, 0xffff0000, v43
	v_mul_f32_e32 v82, v26, v82
	v_mul_f32_e32 v82, v82, v83
	v_and_b32_e32 v83, 0xffff0000, v41
	v_mul_f32_e32 v80, v80, v80
	v_mul_f32_e32 v83, v27, v83
	v_fmac_f32_e32 v80, v78, v78
	v_fmac_f32_e32 v82, v83, v87
	v_fmac_f32_e32 v80, v81, v81
	v_fmac_f32_e32 v80, v82, v82
	v_add_f32_e32 v77, v77, v80
	v_lshlrev_b32_e32 v80, 16, v36
	v_lshlrev_b32_e32 v78, 16, v38
	v_mul_f32_e32 v80, v27, v80
	v_mul_f32_e32 v78, v26, v78
	s_waitcnt lgkmcnt(0)
	v_mul_f32_e32 v80, v80, v92
	v_and_b32_e32 v81, 0xffff0000, v36
	v_fmac_f32_e32 v80, v78, v88
	v_and_b32_e32 v78, 0xffff0000, v38
	v_mul_f32_e32 v81, v27, v81
	v_mul_f32_e32 v78, v26, v78
	v_mul_f32_e32 v81, v81, v93
	v_lshlrev_b32_e32 v82, 16, v37
	v_fmac_f32_e32 v81, v78, v89
	v_lshlrev_b32_e32 v78, 16, v39
	v_mul_f32_e32 v82, v27, v82
	v_mul_f32_e32 v78, v26, v78
	v_mul_f32_e32 v82, v82, v94
	v_and_b32_e32 v83, 0xffff0000, v37
	v_fmac_f32_e32 v82, v78, v90
	v_and_b32_e32 v78, 0xffff0000, v39
	v_mul_f32_e32 v83, v27, v83
	v_mul_f32_e32 v78, v26, v78
	v_mul_f32_e32 v83, v83, v95
	v_fmac_f32_e32 v83, v78, v91
	v_mul_f32_e32 v78, v81, v81
	v_fmac_f32_e32 v78, v80, v80
	v_fmac_f32_e32 v78, v82, v82
	v_fmac_f32_e32 v78, v83, v83
	v_add_f32_e32 v77, v77, v78
	ds_read_b128 v[80:83], v71 offset:40960
	ds_read_b128 v[84:87], v71 offset:8192
	v_lshlrev_b32_e32 v78, 16, v32
	v_mul_f32_e32 v78, v26, v78
	ds_read_b128 v[88:91], v71 offset:41984
	ds_read_b128 v[92:95], v71 offset:9216
	s_waitcnt lgkmcnt(3)
	v_mul_f32_e32 v78, v78, v80
	v_lshlrev_b32_e32 v80, 16, v34
	v_mul_f32_e32 v80, v27, v80
	s_waitcnt lgkmcnt(2)
	v_fmac_f32_e32 v78, v80, v84
	v_and_b32_e32 v80, 0xffff0000, v32
	v_mul_f32_e32 v80, v26, v80
	v_mul_f32_e32 v80, v80, v81
	v_and_b32_e32 v81, 0xffff0000, v34
	v_mul_f32_e32 v81, v27, v81
	v_fmac_f32_e32 v80, v81, v85
	v_lshlrev_b32_e32 v81, 16, v33
	v_mul_f32_e32 v81, v26, v81
	v_mul_f32_e32 v81, v81, v82
	v_lshlrev_b32_e32 v82, 16, v35
	v_mul_f32_e32 v82, v27, v82
	v_fmac_f32_e32 v81, v82, v86
	v_and_b32_e32 v82, 0xffff0000, v33
	v_mul_f32_e32 v82, v26, v82
	v_mul_f32_e32 v82, v82, v83
	v_and_b32_e32 v83, 0xffff0000, v35
	v_mul_f32_e32 v80, v80, v80
	v_mul_f32_e32 v83, v27, v83
	v_fmac_f32_e32 v80, v78, v78
	v_fmac_f32_e32 v82, v83, v87
	v_fmac_f32_e32 v80, v81, v81
	v_fmac_f32_e32 v80, v82, v82
	v_add_f32_e32 v77, v77, v80
	v_lshlrev_b32_e32 v80, 16, v30
	v_lshlrev_b32_e32 v78, 16, v28
	v_mul_f32_e32 v80, v27, v80
	v_mul_f32_e32 v78, v26, v78
	s_waitcnt lgkmcnt(0)
	v_mul_f32_e32 v80, v80, v92
	v_and_b32_e32 v81, 0xffff0000, v30
	v_fmac_f32_e32 v80, v78, v88
	v_and_b32_e32 v78, 0xffff0000, v28
	v_mul_f32_e32 v81, v27, v81
	v_mul_f32_e32 v78, v26, v78
	v_mul_f32_e32 v81, v81, v93
	v_lshlrev_b32_e32 v82, 16, v31
	v_fmac_f32_e32 v81, v78, v89
	v_lshlrev_b32_e32 v78, 16, v29
	v_mul_f32_e32 v82, v27, v82
	v_mul_f32_e32 v78, v26, v78
	v_mul_f32_e32 v82, v82, v94
	v_and_b32_e32 v83, 0xffff0000, v31
	v_fmac_f32_e32 v82, v78, v90
	v_and_b32_e32 v78, 0xffff0000, v29
	v_mul_f32_e32 v83, v27, v83
	v_mul_f32_e32 v78, v26, v78
	v_mul_f32_e32 v83, v83, v95
	v_fmac_f32_e32 v83, v78, v91
	v_mul_f32_e32 v78, v81, v81
	v_fmac_f32_e32 v78, v80, v80
	v_fmac_f32_e32 v78, v82, v82
	v_fmac_f32_e32 v78, v83, v83
	v_add_f32_e32 v77, v77, v78
	ds_read_b128 v[80:83], v71 offset:43008
	ds_read_b128 v[84:87], v71 offset:10240
	v_lshlrev_b32_e32 v78, 16, v22
	v_mul_f32_e32 v78, v26, v78
	ds_read_b128 v[88:91], v71 offset:44032
	ds_read_b128 v[92:95], v71 offset:11264
	s_waitcnt lgkmcnt(3)
; #define LAS __attribute__((address_space(3)))
; __device__ __forceinline__ float bflo(unsigned w) { return __uint_as_float(w << 16); }
; __device__ __forceinline__ float bfhi(unsigned w) { return __uint_as_float(w & 0xffff0000u); }
; template <int MODE> ...
;     ...
;             for (int j = 0; j < 16; ++j) { const f32x4 g = *(const LAS f32x4*)(GP + lo4 + 256 * j), gi = *(const LAS f32x4*)(GI + lo4 + 256 * j);
;                 f32x4 x;
;                 x.x = bflo(pw[j].x) * ri * gi.x + bflo(hw[j].x) * rstd * g.x; x.y = bfhi(pw[j].x) * ri * gi.y + bfhi(hw[j].x) * rstd * g.y;
;                 x.z = bflo(pw[j].y) * ri * gi.z + bflo(hw[j].y) * rstd * g.z; x.w = bfhi(pw[j].y) * ri * gi.w + bfhi(hw[j].y) * rstd * g.w;
;                 if (MODE == 2) *(f32x4*)(xout + (size_t)row * DM + lo4 + 256 * j) = x;
;                 else ss2 += x.x * x.x + x.y * x.y + x.z * x.z + x.w * x.w;
;                 if (j & 1) __builtin_amdgcn_sched_barrier(0); }
;             if (MODE == 1) {
;                 const float rstd2 = rsqrtf(wave_sum(ss2) * (1.f / DM) + EPS);
;                 if (lane == 0) rs_out[row] = rstd2;
	v_mul_f32_e32 v78, v78, v80
	v_lshlrev_b32_e32 v80, 16, v24
	v_mul_f32_e32 v80, v27, v80
	s_waitcnt lgkmcnt(2)
	v_fmac_f32_e32 v78, v80, v84
	v_and_b32_e32 v80, 0xffff0000, v22
	v_mul_f32_e32 v80, v26, v80
	v_mul_f32_e32 v80, v80, v81
	v_and_b32_e32 v81, 0xffff0000, v24
	v_mul_f32_e32 v81, v27, v81
	v_fmac_f32_e32 v80, v81, v85
	v_lshlrev_b32_e32 v81, 16, v23
	v_mul_f32_e32 v81, v26, v81
	v_mul_f32_e32 v81, v81, v82
	v_lshlrev_b32_e32 v82, 16, v25
	v_mul_f32_e32 v82, v27, v82
	v_fmac_f32_e32 v81, v82, v86
	v_and_b32_e32 v82, 0xffff0000, v23
	v_mul_f32_e32 v82, v26, v82
	v_mul_f32_e32 v82, v82, v83
	v_and_b32_e32 v83, 0xffff0000, v25
	v_mul_f32_e32 v80, v80, v80
	v_mul_f32_e32 v83, v27, v83
	v_fmac_f32_e32 v80, v78, v78
	v_fmac_f32_e32 v82, v83, v87
	v_fmac_f32_e32 v80, v81, v81
	v_fmac_f32_e32 v80, v82, v82
	v_add_f32_e32 v77, v77, v80
	v_lshlrev_b32_e32 v80, 16, v20
	v_lshlrev_b32_e32 v78, 16, v18
	v_mul_f32_e32 v80, v27, v80
	v_mul_f32_e32 v78, v26, v78
	s_waitcnt lgkmcnt(0)
	v_mul_f32_e32 v80, v80, v92
	v_and_b32_e32 v81, 0xffff0000, v20
	v_fmac_f32_e32 v80, v78, v88
	v_and_b32_e32 v78, 0xffff0000, v18
	v_mul_f32_e32 v81, v27, v81
	v_mul_f32_e32 v78, v26, v78
	v_mul_f32_e32 v81, v81, v93
	v_lshlrev_b32_e32 v82, 16, v21
	v_fmac_f32_e32 v81, v78, v89
	v_lshlrev_b32_e32 v78, 16, v19
	v_mul_f32_e32 v82, v27, v82
	v_mul_f32_e32 v78, v26, v78
	v_mul_f32_e32 v82, v82, v94
	v_and_b32_e32 v83, 0xffff0000, v21
	v_fmac_f32_e32 v82, v78, v90
	v_and_b32_e32 v78, 0xffff0000, v19
	v_mul_f32_e32 v83, v27, v83
	v_mul_f32_e32 v78, v26, v78
	v_mul_f32_e32 v83, v83, v95
	v_fmac_f32_e32 v83, v78, v91
	v_mul_f32_e32 v78, v81, v81
	v_fmac_f32_e32 v78, v80, v80
	v_fmac_f32_e32 v78, v82, v82
	v_fmac_f32_e32 v78, v83, v83
	v_add_f32_e32 v77, v77, v78
	ds_read_b128 v[80:83], v71 offset:45056
	ds_read_b128 v[84:87], v71 offset:46080
	ds_read_b128 v[88:91], v71 offset:12288
	ds_read_b128 v[92:95], v71 offset:13312
	v_lshlrev_b32_e32 v103, 16, v14
	v_lshlrev_b32_e32 v102, 16, v12
	v_lshlrev_b32_e32 v96, 16, v10
	v_lshlrev_b32_e32 v97, 16, v16
	v_pk_mul_f32 v[102:103], v[26:27], v[102:103] op_sel:[1,0] op_sel_hi:[0,1]
	s_waitcnt lgkmcnt(0)
	v_mov_b32_e32 v104, v92
	v_mov_b32_e32 v105, v80
	v_pk_mul_f32 v[96:97], v[26:27], v[96:97]
	v_mov_b32_e32 v98, v84
	v_mov_b32_e32 v99, v88
	v_pk_mul_f32 v[102:103], v[102:103], v[104:105]
	v_mov_b32_e32 v88, v85
	v_and_b32_e32 v85, 0xffff0000, v14
	v_and_b32_e32 v84, 0xffff0000, v12
	v_pk_fma_f32 v[96:97], v[96:97], v[98:99], v[102:103]
	v_and_b32_e32 v99, 0xffff0000, v16
	v_and_b32_e32 v98, 0xffff0000, v10
	v_pk_mul_f32 v[84:85], v[26:27], v[84:85] op_sel:[1,0] op_sel_hi:[0,1]
	v_mov_b32_e32 v80, v93
	v_pk_mul_f32 v[98:99], v[26:27], v[98:99]
	v_pk_mul_f32 v[80:81], v[84:85], v[80:81]
	v_lshlrev_b32_e32 v93, 16, v15
	v_lshlrev_b32_e32 v92, 16, v13
	v_pk_fma_f32 v[80:81], v[98:99], v[88:89], v[80:81]
	v_lshlrev_b32_e32 v84, 16, v11
	v_lshlrev_b32_e32 v85, 16, v17
	v_pk_mul_f32 v[92:93], v[26:27], v[92:93] op_sel:[1,0] op_sel_hi:[0,1]
	v_mov_b32_e32 v98, v94
	v_mov_b32_e32 v99, v82
	v_pk_mul_f32 v[84:85], v[26:27], v[84:85]
	v_mov_b32_e32 v88, v86
	v_mov_b32_e32 v89, v90
	v_pk_mul_f32 v[92:93], v[92:93], v[98:99]
	v_mov_b32_e32 v90, v87
	v_and_b32_e32 v87, 0xffff0000, v15
	v_and_b32_e32 v86, 0xffff0000, v13
	v_pk_fma_f32 v[84:85], v[84:85], v[88:89], v[92:93]
	v_and_b32_e32 v89, 0xffff0000, v17
	v_and_b32_e32 v88, 0xffff0000, v11
	v_pk_mul_f32 v[86:87], v[26:27], v[86:87] op_sel:[1,0] op_sel_hi:[0,1]
	v_mov_b32_e32 v82, v95
	v_pk_mul_f32 v[80:81], v[80:81], v[80:81]
	v_pk_mul_f32 v[88:89], v[26:27], v[88:89]
	v_pk_mul_f32 v[82:83], v[86:87], v[82:83]
	v_pk_fma_f32 v[80:81], v[96:97], v[96:97], v[80:81]
	v_pk_fma_f32 v[82:83], v[88:89], v[90:91], v[82:83]
	v_pk_fma_f32 v[80:81], v[84:85], v[84:85], v[80:81]
	s_nop 0
	v_pk_fma_f32 v[80:81], v[82:83], v[82:83], v[80:81]
	s_nop 0
	v_add_f32_e32 v77, v77, v81
	v_add_f32_e32 v77, v77, v80
	ds_read_b128 v[80:83], v71 offset:47104
	ds_read_b128 v[84:87], v71 offset:48128
	ds_read_b128 v[88:91], v71 offset:14336
	ds_read_b128 v[92:95], v71 offset:15360
	v_lshlrev_b32_e32 v103, 16, v6
	v_lshlrev_b32_e32 v102, 16, v4
	v_lshlrev_b32_e32 v96, 16, v2
	v_lshlrev_b32_e32 v97, 16, v8
	v_pk_mul_f32 v[102:103], v[26:27], v[102:103] op_sel:[1,0] op_sel_hi:[0,1]
	s_waitcnt lgkmcnt(0)
	v_mov_b32_e32 v104, v92
	v_mov_b32_e32 v105, v80
	v_pk_mul_f32 v[96:97], v[26:27], v[96:97]
	v_mov_b32_e32 v98, v84
	v_mov_b32_e32 v99, v88
	v_pk_mul_f32 v[102:103], v[102:103], v[104:105]
	v_mov_b32_e32 v88, v85
	v_and_b32_e32 v85, 0xffff0000, v6
	v_and_b32_e32 v84, 0xffff0000, v4
	v_pk_fma_f32 v[96:97], v[96:97], v[98:99], v[102:103]
	v_and_b32_e32 v99, 0xffff0000, v8
	v_and_b32_e32 v98, 0xffff0000, v2
	v_pk_mul_f32 v[84:85], v[26:27], v[84:85] op_sel:[1,0] op_sel_hi:[0,1]
	v_mov_b32_e32 v80, v93
	v_pk_mul_f32 v[98:99], v[26:27], v[98:99]
	v_pk_mul_f32 v[80:81], v[84:85], v[80:81]
	v_lshlrev_b32_e32 v93, 16, v7
	v_lshlrev_b32_e32 v92, 16, v5
	v_pk_fma_f32 v[80:81], v[98:99], v[88:89], v[80:81]
	v_lshlrev_b32_e32 v84, 16, v3
	v_lshlrev_b32_e32 v85, 16, v9
	v_pk_mul_f32 v[92:93], v[26:27], v[92:93] op_sel:[1,0] op_sel_hi:[0,1]
	v_mov_b32_e32 v98, v94
	v_mov_b32_e32 v99, v82
	v_pk_mul_f32 v[84:85], v[26:27], v[84:85]
	v_mov_b32_e32 v88, v86
	v_mov_b32_e32 v89, v90
	v_pk_mul_f32 v[92:93], v[92:93], v[98:99]
	v_mov_b32_e32 v90, v87
	v_and_b32_e32 v87, 0xffff0000, v7
	v_and_b32_e32 v86, 0xffff0000, v5
	v_pk_fma_f32 v[84:85], v[84:85], v[88:89], v[92:93]
	v_and_b32_e32 v89, 0xffff0000, v9
	v_and_b32_e32 v88, 0xffff0000, v3
	v_pk_mul_f32 v[86:87], v[26:27], v[86:87] op_sel:[1,0] op_sel_hi:[0,1]
	v_mov_b32_e32 v82, v95
	v_pk_mul_f32 v[80:81], v[80:81], v[80:81]
	v_pk_mul_f32 v[88:89], v[26:27], v[88:89]
	v_pk_mul_f32 v[82:83], v[86:87], v[82:83]
	v_pk_fma_f32 v[80:81], v[96:97], v[96:97], v[80:81]
	v_pk_fma_f32 v[82:83], v[88:89], v[90:91], v[82:83]
	v_pk_fma_f32 v[80:81], v[84:85], v[84:85], v[80:81]
	s_nop 0
	v_pk_fma_f32 v[80:81], v[82:83], v[82:83], v[80:81]
	s_nop 0
	v_add_f32_e32 v77, v77, v81
	v_add_f32_e32 v77, v77, v80
	ds_bpermute_b32 v70, v70, v77
	s_waitcnt lgkmcnt(0)
	v_add_f32_e32 v70, v77, v70
	ds_bpermute_b32 v72, v72, v70
	s_waitcnt lgkmcnt(0)
	v_add_f32_e32 v70, v70, v72
	ds_bpermute_b32 v72, v73, v70
	s_waitcnt lgkmcnt(0)
	v_add_f32_e32 v70, v70, v72
	ds_bpermute_b32 v72, v74, v70
	s_waitcnt lgkmcnt(0)
	v_add_f32_e32 v70, v70, v72
	ds_bpermute_b32 v72, v75, v70
	s_waitcnt lgkmcnt(0)
	v_add_f32_e32 v70, v70, v72
	ds_bpermute_b32 v72, v76, v70
	s_waitcnt lgkmcnt(0)
	v_add_f32_e32 v70, v70, v72
	v_fmamk_f32 v70, v70, 0x39800000, v100
	v_mul_f32_e32 v72, 0x4b800000, v70
	v_cmp_gt_f32_e32 vcc, s66, v70
	s_nop 1
	v_cndmask_b32_e32 v70, v70, v72, vcc
	v_rsq_f32_e32 v70, v70
	s_nop 0
	v_mul_f32_e32 v72, 0x45800000, v70
	v_cndmask_b32_e32 v70, v70, v72, vcc
	s_and_saveexec_b64 s[6:7], s[4:5]
	s_cbranch_execz .LBB0_1118
	global_store_dword v79, v70, s[62:63]
	s_branch .LBB0_1118

; #define LAS __attribute__((address_space(3)))
; template <int MODE> ...
;     ...
;     LAS float* GP = (LAS float*)lds; LAS float* GN = (LAS float*)(lds + 16384); LAS float* GI = (LAS float*)(lds + 32768);
;     __syncthreads();
; #pragma unroll
;     for (int i = 0; i < 2; ++i) { const int o = 4 * (tid + NTHREADS * i);
;         if (MODE != 0) { *(LAS f32x4*)(GP + o) = *(const f32x4*)(gpost + o); const f32x4 g = *(const f32x4*)(gprev + o); *(LAS f32x4*)(GI + o) = (f32x4){1.f / g.x, 1.f / g.y, 1.f / g.z, 1.f / g.w}; }
;         if (MODE != 2) *(LAS f32x4*)(GN + o) = *(const f32x4*)(gpre + o); }
;     __syncthreads();
.LBB0_1610:
	s_cmp_gt_i32 s36, 14
	s_cselect_b64 s[6:7], -1, 0
	s_xor_b64 s[4:5], s[4:5], -1
	s_or_b64 s[4:5], s[6:7], s[4:5]
	s_and_b64 vcc, exec, s[4:5]
	s_cbranch_vccnz .LBB0_1616
	s_mov_b64 s[12:13], 0
	s_waitcnt vmcnt(0)
	v_mbcnt_lo_u32_b32 v2, -1, 0
	v_mbcnt_hi_u32_b32 v2, -1, v2
	s_load_dwordx4 s[4:7], s[0:1], 0xa8
	s_load_dwordx2 s[8:9], s[0:1], 0x10
	v_lshlrev_b32_e32 v0, 2, v2
	v_lshl_add_u32 v24, s89, 8, v0
	v_ashrrev_i32_e32 v25, 31, v24
	v_lshlrev_b64 v[20:21], 2, v[24:25]
	v_add_u32_e32 v12, 0x800, v24
	s_waitcnt lgkmcnt(0)
	v_lshl_add_u64 v[8:9], s[4:5], 0, v[20:21]
	v_ashrrev_i32_e32 v13, 31, v12
	s_barrier
	v_lshl_add_u64 v[4:5], s[6:7], 0, v[20:21]
	global_load_dwordx4 v[8:11], v[8:9], off
	v_lshlrev_b64 v[26:27], 2, v[12:13]
	global_load_dwordx4 v[4:7], v[4:5], off
	v_lshl_add_u64 v[12:13], s[6:7], 0, v[26:27]
	v_lshl_add_u64 v[16:17], s[4:5], 0, v[26:27]
	global_load_dwordx4 v[12:15], v[12:13], off
	s_add_u32 s4, s8, 0x4000
	global_load_dwordx4 v[16:19], v[16:17], off
	s_addc_u32 s5, s9, 0
	v_lshl_add_u64 v[20:21], s[4:5], 0, v[20:21]
	global_load_dwordx4 v[20:23], v[20:21], off
	v_lshl_add_u32 v1, v24, 2, 0
	v_lshl_add_u64 v[24:25], s[4:5], 0, v[26:27]
	global_load_dwordx4 v[24:27], v[24:25], off
	s_cmpk_gt_i32 s40, 0x1fff
	s_waitcnt vmcnt(5)
	v_div_scale_f32 v3, s[4:5], v8, v8, 1.0
	s_waitcnt vmcnt(4)
	ds_write_b128 v1, v[4:7]
	v_div_scale_f32 v5, s[4:5], v9, v9, 1.0
	v_rcp_f32_e32 v31, v3
	v_div_scale_f32 v7, s[6:7], v10, v10, 1.0
	v_rcp_f32_e32 v32, v5
	s_waitcnt vmcnt(3)
	ds_write_b128 v1, v[12:15] offset:8192
	s_waitcnt vmcnt(2)
	v_div_scale_f32 v12, s[10:11], v16, v16, 1.0
	v_div_scale_f32 v29, s[8:9], v11, v11, 1.0
	v_rcp_f32_e32 v33, v7
	v_rcp_f32_e32 v15, v12
	v_rcp_f32_e32 v34, v29
	s_waitcnt vmcnt(1)
	ds_write_b128 v1, v[20:23] offset:16384
	v_fma_f32 v21, -v3, v31, 1.0
	v_div_scale_f32 v4, vcc, 1.0, v8, 1.0
	v_fma_f32 v22, -v5, v32, 1.0
	v_fmac_f32_e32 v31, v21, v31
	v_div_scale_f32 v6, s[4:5], 1.0, v9, 1.0
	v_fma_f32 v23, -v7, v33, 1.0
	v_fmac_f32_e32 v32, v22, v32
	v_fma_f32 v21, -v12, v15, 1.0
	v_mul_f32_e32 v22, v4, v31
	v_div_scale_f32 v28, s[6:7], 1.0, v10, 1.0
	v_fma_f32 v35, -v29, v34, 1.0
	v_fmac_f32_e32 v33, v23, v33
	v_mul_f32_e32 v23, v6, v32
	v_fmac_f32_e32 v15, v21, v15
	v_fma_f32 v21, -v3, v22, v4
	v_div_scale_f32 v30, s[8:9], 1.0, v11, 1.0
	v_fmac_f32_e32 v34, v35, v34
	v_mul_f32_e32 v35, v28, v33
	v_fma_f32 v37, -v5, v23, v6
	v_fmac_f32_e32 v22, v21, v31
	v_div_scale_f32 v13, s[10:11], 1.0, v16, 1.0
	v_mul_f32_e32 v36, v30, v34
	v_fma_f32 v38, -v7, v35, v28
	v_fmac_f32_e32 v23, v37, v32
	v_fma_f32 v3, -v3, v22, v4
	v_div_scale_f32 v14, s[14:15], v17, v17, 1.0
	v_fma_f32 v39, -v29, v36, v30
	v_mul_f32_e32 v40, v13, v15
	v_fmac_f32_e32 v35, v38, v33
	v_fma_f32 v5, -v5, v23, v6
	v_div_fmas_f32 v3, v3, v31, v22
	s_mov_b64 vcc, s[4:5]
	v_rcp_f32_e32 v20, v14
	v_fmac_f32_e32 v36, v39, v34
	v_fma_f32 v21, -v12, v40, v13
	v_fma_f32 v6, -v7, v35, v28
	v_div_fixup_f32 v4, v3, v8, 1.0
	v_div_fmas_f32 v3, v5, v32, v23
	s_mov_b64 vcc, s[6:7]
	v_fma_f32 v7, -v29, v36, v30
	v_fmac_f32_e32 v40, v21, v15
	v_div_fixup_f32 v5, v3, v9, 1.0
	v_div_fmas_f32 v3, v6, v33, v35
	s_mov_b64 vcc, s[8:9]
	v_fma_f32 v12, -v12, v40, v13
	v_div_fixup_f32 v6, v3, v10, 1.0
	v_div_fmas_f32 v3, v7, v34, v36
	s_mov_b64 vcc, s[10:11]
	v_div_fixup_f32 v7, v3, v11, 1.0
	v_div_fmas_f32 v3, v12, v15, v40
	ds_write_b128 v1, v[4:7] offset:32768
	v_div_fixup_f32 v4, v3, v16, 1.0
	v_fma_f32 v3, -v14, v20, 1.0
	v_fmac_f32_e32 v20, v3, v20
	v_div_scale_f32 v3, vcc, 1.0, v17, 1.0
	v_mul_f32_e32 v5, v3, v20
	v_fma_f32 v6, -v14, v5, v3
	v_fmac_f32_e32 v5, v6, v20
	v_div_scale_f32 v6, s[4:5], v18, v18, 1.0
	v_rcp_f32_e32 v7, v6
	v_fma_f32 v3, -v14, v5, v3
	v_div_fmas_f32 v3, v3, v20, v5
	v_div_fixup_f32 v5, v3, v17, 1.0
	v_fma_f32 v3, -v6, v7, 1.0
	v_fmac_f32_e32 v7, v3, v7
	v_div_scale_f32 v3, vcc, 1.0, v18, 1.0
	v_mul_f32_e32 v8, v3, v7
	v_fma_f32 v9, -v6, v8, v3
	v_fmac_f32_e32 v8, v9, v7
	v_div_scale_f32 v9, s[4:5], v19, v19, 1.0
	v_rcp_f32_e32 v10, v9
	v_fma_f32 v3, -v6, v8, v3
	v_div_fmas_f32 v3, v3, v7, v8
	v_div_fixup_f32 v6, v3, v18, 1.0
	v_fma_f32 v3, -v9, v10, 1.0
	v_fmac_f32_e32 v10, v3, v10
	v_div_scale_f32 v3, vcc, 1.0, v19, 1.0
	v_mul_f32_e32 v7, v3, v10
	v_fma_f32 v8, -v9, v7, v3
	v_fmac_f32_e32 v7, v8, v10
	v_fma_f32 v3, -v9, v7, v3
	v_div_fmas_f32 v3, v3, v10, v7
	v_div_fixup_f32 v7, v3, v19, 1.0
	ds_write_b128 v1, v[4:7] offset:40960
	s_waitcnt vmcnt(0)
	ds_write_b128 v1, v[24:27] offset:24576
	s_waitcnt lgkmcnt(0)
	s_barrier
; #define LAS __attribute__((address_space(3)))
; __device__ __forceinline__ unsigned pk2(float lo, float hi) { const f32x2c v = {lo, hi}; return __builtin_bit_cast(unsigned, __builtin_convertvector(v, bf16x2c)); }
; template <int MODE> ...
;     ...
;     const int lo4 = 4 * lane;
; #pragma unroll 1
;     for (int row = gw; row < SEQ; row += NGW) {
;         asm volatile("" ::: "memory");
;         if (MODE == 0) {
;             const float* xr = xin + (size_t)row * DM; bf16* nw = xn_out + (size_t)row * DM;
;             f32x4 xv[16]; float ss = 0.f;
; #pragma unroll
;             for (int j = 0; j < 16; ++j) { xv[j] = *(const f32x4*)(xr + lo4 + 256 * j); ss += xv[j].x * xv[j].x + xv[j].y * xv[j].y + xv[j].z * xv[j].z + xv[j].w * xv[j].w; }
;             const float rstd = rsqrtf(wave_sum(ss) * (1.f / DM) + EPS);
;             if (lane == 0) rs_out[row] = rstd;
;             asm volatile("" ::: "memory");
; #pragma unroll
;             for (int j = 0; j < 16; ++j) { const f32x4 g = *(const LAS f32x4*)(GN + lo4 + 256 * j);
;                 v2u w; w.x = pk2(xv[j].x * rstd * g.x, xv[j].y * rstd * g.y); w.y = pk2(xv[j].z * rstd * g.z, xv[j].w * rstd * g.w);
;                 *(v2u*)(nw + lo4 + 256 * j) = w; }
;         } else {
;             const bf16* pr = xn + (size_t)row * DM; bf16* pw_out = xn_out + (size_t)row * DM; const bf16* hr = hb + (size_t)row * DM;
;             v2u pw[16], hw[16]; float ss = 0.f;
; #pragma unroll
;             for (int j = 0; j < 16; ++j) { pw[j] = *(const v2u*)(pr + lo4 + 256 * j); hw[j] = *(const v2u*)(hr + lo4 + 256 * j); }
	s_cbranch_scc1 .LBB0_1616
	s_load_dwordx2 s[6:7], s[0:1], 0xe8
	s_ashr_i32 s41, s40, 31
	s_lshl_b64 s[8:9], s[40:41], 2
	v_ashrrev_i32_e32 v1, 31, v0
	v_cmp_eq_u32_e64 s[4:5], 0, v2
	s_waitcnt lgkmcnt(0)
	s_add_u32 s8, s6, s8
	s_addc_u32 s9, s7, s9
	s_add_u32 s64, s8, 0x2c0000
	s_addc_u32 s65, s9, 0
	s_ashr_i32 s39, s38, 31
	s_lshl_b64 s[8:9], s[38:39], 2
	s_lshl_b64 s[10:11], s[40:41], 13
	s_add_u32 s6, s6, s10
	s_addc_u32 s7, s7, s11
	v_mbcnt_lo_u32_b32 v2, -1, 0
	v_lshl_add_u32 v71, v0, 2, 0
	v_lshl_add_u64 v[0:1], v[0:1], 1, s[6:7]
	s_lshl_b64 s[10:11], s[38:39], 13
	s_mov_b64 s[14:15], 0x3000000
	s_mov_b64 s[18:19], 0x3000200
	s_mov_b64 s[20:21], 0x3000400
	s_mov_b64 s[22:23], 0x3000600
	s_mov_b64 s[24:25], 0x3000800
	s_mov_b64 s[26:27], 0x3000a00
	s_mov_b64 s[42:43], 0x3000c00
	s_mov_b64 s[44:45], 0x3000e00
	s_mov_b64 s[46:47], 0x3001000
	s_mov_b32 s39, 0x3001000
	s_mov_b32 s41, 0x7001000
	s_mov_b64 s[48:49], 0x3001200
	s_mov_b64 s[50:51], 0x3001400
	s_mov_b64 s[52:53], 0x3001600
	s_mov_b64 s[54:55], 0x3001800
	s_mov_b64 s[56:57], 0x3001a00
	s_mov_b64 s[58:59], 0x3001c00
	s_mov_b64 s[60:61], 0x3001e00
	v_mov_b32_e32 v98, 0
	v_mov_b32_e32 v99, 0x358637bd
	s_mov_b32 s66, 0x800000
	v_mbcnt_hi_u32_b32 v100, -1, v2
	s_mov_b32 s67, s40
	v_lshl_add_u64 v[214:215], v[0:1], 0, s[12:13]
	s_add_u32 s100, s64, s12
	s_addc_u32 s101, s65, s13
	v_add_co_u32_e32 v206, vcc, 0x3000000, v214
	s_nop 1
	v_addc_co_u32_e32 v207, vcc, 0, v215, vcc
	v_add_co_u32_e32 v208, vcc, 0x7000000, v214
	s_nop 1
	v_addc_co_u32_e32 v209, vcc, 0, v215, vcc
	v_add_co_u32_e32 v210, vcc, s39, v214
	s_nop 1
	v_addc_co_u32_e32 v211, vcc, 0, v215, vcc
	v_add_co_u32_e32 v212, vcc, s41, v214
	s_nop 1
	v_addc_co_u32_e32 v213, vcc, 0, v215, vcc
	global_load_dwordx2 v[198:199], v[208:209], off
	global_load_dwordx2 v[192:193], v[208:209], off offset:512
	global_load_dwordx2 v[190:191], v[208:209], off offset:1024
	global_load_dwordx2 v[186:187], v[208:209], off offset:1536
	global_load_dwordx2 v[182:183], v[208:209], off offset:2048
	global_load_dwordx2 v[180:181], v[208:209], off offset:2560
	global_load_dwordx2 v[176:177], v[208:209], off offset:3072
	global_load_dwordx2 v[168:169], v[210:211], off
	global_load_dwordx2 v[164:165], v[210:211], off offset:512
	global_load_dwordx2 v[160:161], v[210:211], off offset:1024
	global_load_dwordx2 v[156:157], v[210:211], off offset:1536
	global_load_dwordx2 v[170:171], v[212:213], off
	global_load_dwordx2 v[166:167], v[212:213], off offset:512
	global_load_dwordx2 v[162:163], v[212:213], off offset:1024
	global_load_dwordx2 v[158:159], v[212:213], off offset:1536
	global_load_dwordx2 v[172:173], v[208:209], off offset:3584
	global_load_dwordx2 v[152:153], v[210:211], off offset:2048
	global_load_dwordx2 v[148:149], v[210:211], off offset:2560
	global_load_dwordx2 v[144:145], v[210:211], off offset:3072
	global_load_dwordx2 v[140:141], v[210:211], off offset:3584
	global_load_dwordx2 v[154:155], v[212:213], off offset:2048
	global_load_dwordx2 v[150:151], v[212:213], off offset:2560
	global_load_dwordx2 v[146:147], v[212:213], off offset:3072
	global_load_dwordx2 v[142:143], v[212:213], off offset:3584
	global_load_dword v216, v98, s[100:101]
	global_load_dwordx2 v[202:203], v[206:207], off
	global_load_dwordx2 v[200:201], v[206:207], off offset:512
	global_load_dwordx2 v[196:197], v[206:207], off offset:1024
	global_load_dwordx2 v[194:195], v[206:207], off offset:1536
	global_load_dwordx2 v[188:189], v[206:207], off offset:2048
	global_load_dwordx2 v[184:185], v[206:207], off offset:2560
	global_load_dwordx2 v[178:179], v[206:207], off offset:3072
	global_load_dwordx2 v[174:175], v[206:207], off offset:3584
	s_waitcnt vmcnt(0)
	s_branch .Lnpf_body_2

; #define LAS __attribute__((address_space(3)))
; template <int MODE> ...
;     ...
;     LAS float* GP = (LAS float*)lds; LAS float* GN = (LAS float*)(lds + 16384); LAS float* GI = (LAS float*)(lds + 32768);
;     __syncthreads();
; #pragma unroll
;     for (int i = 0; i < 2; ++i) { const int o = 4 * (tid + NTHREADS * i);
;         if (MODE != 0) { *(LAS f32x4*)(GP + o) = *(const f32x4*)(gpost + o); const f32x4 g = *(const f32x4*)(gprev + o); *(LAS f32x4*)(GI + o) = (f32x4){1.f / g.x, 1.f / g.y, 1.f / g.z, 1.f / g.w}; }
;         if (MODE != 2) *(LAS f32x4*)(GN + o) = *(const f32x4*)(gpre + o); }
;     __syncthreads();
.LBB0_1984:
	s_cmp_gt_i32 s36, 18
	s_cselect_b64 s[6:7], -1, 0
	s_xor_b64 s[4:5], s[4:5], -1
	s_or_b64 s[4:5], s[6:7], s[4:5]
	s_and_b64 vcc, exec, s[4:5]
	s_cbranch_vccnz .LBB0_1990
	s_mov_b64 s[12:13], 0
	s_waitcnt vmcnt(0)
	v_mbcnt_lo_u32_b32 v2, -1, 0
	v_mbcnt_hi_u32_b32 v2, -1, v2
	s_load_dwordx4 s[4:7], s[0:1], 0x10
	s_load_dwordx2 s[8:9], s[0:1], 0x70
	v_lshlrev_b32_e32 v0, 2, v2
	v_lshl_add_u32 v24, s89, 8, v0
	v_ashrrev_i32_e32 v25, 31, v24
	s_waitcnt lgkmcnt(0)
	s_add_u32 s4, s4, 0x4000
	s_addc_u32 s5, s5, 0
	v_lshlrev_b64 v[20:21], 2, v[24:25]
	v_lshl_add_u64 v[4:5], s[4:5], 0, v[20:21]
	v_add_u32_e32 v8, 0x800, v24
	s_barrier
	global_load_dwordx4 v[4:7], v[4:5], off
	v_ashrrev_i32_e32 v9, 31, v8
	v_lshlrev_b64 v[26:27], 2, v[8:9]
	v_lshl_add_u64 v[8:9], s[4:5], 0, v[26:27]
	s_add_u32 s4, s6, 0x4000
	s_addc_u32 s5, s7, 0
	s_add_u32 s6, s8, 0x4000
	v_lshl_add_u64 v[22:23], s[4:5], 0, v[20:21]
	global_load_dwordx4 v[8:11], v[8:9], off
	v_lshl_add_u64 v[28:29], s[4:5], 0, v[26:27]
	s_addc_u32 s7, s9, 0
	global_load_dwordx4 v[12:15], v[22:23], off
	global_load_dwordx4 v[16:19], v[28:29], off
	v_lshl_add_u64 v[20:21], s[6:7], 0, v[20:21]
	global_load_dwordx4 v[20:23], v[20:21], off
	v_lshl_add_u32 v1, v24, 2, 0
	v_lshl_add_u64 v[24:25], s[6:7], 0, v[26:27]
	global_load_dwordx4 v[24:27], v[24:25], off
	s_cmpk_gt_i32 s40, 0x1fff
	s_waitcnt vmcnt(3)
	ds_write_b128 v1, v[12:15]
	s_waitcnt vmcnt(2)
	ds_write_b128 v1, v[16:19] offset:8192
	s_waitcnt vmcnt(1)
	ds_write_b128 v1, v[20:23] offset:16384
	v_div_scale_f32 v3, s[4:5], v4, v4, 1.0
	v_div_scale_f32 v29, s[4:5], v5, v5, 1.0
	v_rcp_f32_e32 v37, v3
	v_div_scale_f32 v31, s[6:7], v6, v6, 1.0
	v_rcp_f32_e32 v38, v29
	v_div_scale_f32 v33, s[8:9], v7, v7, 1.0
	v_rcp_f32_e32 v39, v31
	v_rcp_f32_e32 v40, v33
	v_fma_f32 v12, -v3, v37, 1.0
	v_div_scale_f32 v28, vcc, 1.0, v4, 1.0
	v_fma_f32 v13, -v29, v38, 1.0
	v_fmac_f32_e32 v37, v12, v37
	v_div_scale_f32 v30, s[4:5], 1.0, v5, 1.0
	v_fma_f32 v14, -v31, v39, 1.0
	v_fmac_f32_e32 v38, v13, v38
	v_mul_f32_e32 v12, v28, v37
	v_div_scale_f32 v32, s[6:7], 1.0, v6, 1.0
	v_fma_f32 v15, -v33, v40, 1.0
	v_fmac_f32_e32 v39, v14, v39
	v_mul_f32_e32 v13, v30, v38
	v_fma_f32 v17, -v3, v12, v28
	v_div_scale_f32 v34, s[8:9], 1.0, v7, 1.0
	v_fmac_f32_e32 v40, v15, v40
	v_mul_f32_e32 v14, v32, v39
	v_fma_f32 v18, -v29, v13, v30
	v_fmac_f32_e32 v12, v17, v37
	v_div_scale_f32 v35, s[10:11], v8, v8, 1.0
	v_mul_f32_e32 v15, v34, v40
	v_fma_f32 v19, -v31, v14, v32
	v_fmac_f32_e32 v13, v18, v38
	v_fma_f32 v3, -v3, v12, v28
	v_rcp_f32_e32 v41, v35
	v_fma_f32 v20, -v33, v15, v34
	v_fmac_f32_e32 v14, v19, v39
	v_fma_f32 v17, -v29, v13, v30
	v_div_fmas_f32 v3, v3, v37, v12
	s_mov_b64 vcc, s[4:5]
	v_fmac_f32_e32 v15, v20, v40
	v_fma_f32 v18, -v31, v14, v32
	v_div_fixup_f32 v4, v3, v4, 1.0
	v_div_fmas_f32 v3, v17, v38, v13
	s_mov_b64 vcc, s[6:7]
	v_fma_f32 v19, -v33, v15, v34
	v_div_fixup_f32 v5, v3, v5, 1.0
	v_div_fmas_f32 v3, v18, v39, v14
	s_mov_b64 vcc, s[8:9]
	v_div_fixup_f32 v6, v3, v6, 1.0
	v_div_fmas_f32 v3, v19, v40, v15
	v_fma_f32 v16, -v35, v41, 1.0
	v_div_fixup_f32 v7, v3, v7, 1.0
	v_div_scale_f32 v3, s[4:5], v9, v9, 1.0
	v_div_scale_f32 v36, s[10:11], 1.0, v8, 1.0
	v_fmac_f32_e32 v41, v16, v41
	ds_write_b128 v1, v[4:7] offset:32768
	v_rcp_f32_e32 v5, v3
	v_mul_f32_e32 v16, v36, v41
	v_fma_f32 v21, -v35, v16, v36
	v_fmac_f32_e32 v16, v21, v41
	v_fma_f32 v20, -v35, v16, v36
	s_mov_b64 vcc, s[10:11]
	v_fma_f32 v6, -v3, v5, 1.0
	v_div_fmas_f32 v4, v20, v41, v16
	v_fmac_f32_e32 v5, v6, v5
	v_div_scale_f32 v6, vcc, 1.0, v9, 1.0
	v_mul_f32_e32 v7, v6, v5
	v_div_fixup_f32 v4, v4, v8, 1.0
	v_fma_f32 v8, -v3, v7, v6
	v_fmac_f32_e32 v7, v8, v5
	v_fma_f32 v3, -v3, v7, v6
	v_div_scale_f32 v6, s[4:5], v10, v10, 1.0
	v_rcp_f32_e32 v8, v6
	v_div_fmas_f32 v3, v3, v5, v7
	v_div_fixup_f32 v5, v3, v9, 1.0
	v_fma_f32 v3, -v6, v8, 1.0
	v_fmac_f32_e32 v8, v3, v8
	v_div_scale_f32 v3, vcc, 1.0, v10, 1.0
	v_mul_f32_e32 v7, v3, v8
	v_fma_f32 v9, -v6, v7, v3
	v_fmac_f32_e32 v7, v9, v8
	v_div_scale_f32 v9, s[4:5], v11, v11, 1.0
	v_rcp_f32_e32 v12, v9
	v_fma_f32 v3, -v6, v7, v3
	v_div_fmas_f32 v3, v3, v8, v7
	v_div_fixup_f32 v6, v3, v10, 1.0
	v_fma_f32 v3, -v9, v12, 1.0
	v_fmac_f32_e32 v12, v3, v12
	v_div_scale_f32 v3, vcc, 1.0, v11, 1.0
	v_mul_f32_e32 v7, v3, v12
	v_fma_f32 v8, -v9, v7, v3
	v_fmac_f32_e32 v7, v8, v12
	v_fma_f32 v3, -v9, v7, v3
	v_div_fmas_f32 v3, v3, v12, v7
	v_div_fixup_f32 v7, v3, v11, 1.0
	ds_write_b128 v1, v[4:7] offset:40960
	s_waitcnt vmcnt(0)
	ds_write_b128 v1, v[24:27] offset:24576
	s_waitcnt lgkmcnt(0)
	s_barrier
; #define LAS __attribute__((address_space(3)))
; __device__ __forceinline__ unsigned pk2(float lo, float hi) { const f32x2c v = {lo, hi}; return __builtin_bit_cast(unsigned, __builtin_convertvector(v, bf16x2c)); }
; template <int MODE> ...
;     ...
;     const int lo4 = 4 * lane;
; #pragma unroll 1
;     for (int row = gw; row < SEQ; row += NGW) {
;         asm volatile("" ::: "memory");
;         if (MODE == 0) {
;             const float* xr = xin + (size_t)row * DM; bf16* nw = xn_out + (size_t)row * DM;
;             f32x4 xv[16]; float ss = 0.f;
; #pragma unroll
;             for (int j = 0; j < 16; ++j) { xv[j] = *(const f32x4*)(xr + lo4 + 256 * j); ss += xv[j].x * xv[j].x + xv[j].y * xv[j].y + xv[j].z * xv[j].z + xv[j].w * xv[j].w; }
;             const float rstd = rsqrtf(wave_sum(ss) * (1.f / DM) + EPS);
;             if (lane == 0) rs_out[row] = rstd;
;             asm volatile("" ::: "memory");
; #pragma unroll
;             for (int j = 0; j < 16; ++j) { const f32x4 g = *(const LAS f32x4*)(GN + lo4 + 256 * j);
;                 v2u w; w.x = pk2(xv[j].x * rstd * g.x, xv[j].y * rstd * g.y); w.y = pk2(xv[j].z * rstd * g.z, xv[j].w * rstd * g.w);
;                 *(v2u*)(nw + lo4 + 256 * j) = w; }
;         } else {
;             const bf16* pr = xn + (size_t)row * DM; bf16* pw_out = xn_out + (size_t)row * DM; const bf16* hr = hb + (size_t)row * DM;
;             v2u pw[16], hw[16]; float ss = 0.f;
; #pragma unroll
;             for (int j = 0; j < 16; ++j) { pw[j] = *(const v2u*)(pr + lo4 + 256 * j); hw[j] = *(const v2u*)(hr + lo4 + 256 * j); }
	s_cbranch_scc1 .LBB0_1990
	s_load_dwordx2 s[6:7], s[0:1], 0xe8
	s_ashr_i32 s41, s40, 31
	s_lshl_b64 s[8:9], s[40:41], 2
	v_ashrrev_i32_e32 v1, 31, v0
	v_cmp_eq_u32_e64 s[4:5], 0, v2
	s_waitcnt lgkmcnt(0)
	s_add_u32 s8, s6, s8
	s_addc_u32 s9, s7, s9
	s_add_u32 s64, s8, 0x2c0000
	s_addc_u32 s65, s9, 0
	s_ashr_i32 s39, s38, 31
	s_lshl_b64 s[8:9], s[38:39], 2
	s_lshl_b64 s[10:11], s[40:41], 13
	s_add_u32 s6, s6, s10
	s_addc_u32 s7, s7, s11
	v_mbcnt_lo_u32_b32 v2, -1, 0
	v_lshl_add_u32 v71, v0, 2, 0
	v_lshl_add_u64 v[0:1], v[0:1], 1, s[6:7]
	s_lshl_b64 s[10:11], s[38:39], 13
	s_mov_b64 s[14:15], 0x3000000
	s_mov_b64 s[18:19], 0x3000200
	s_mov_b64 s[20:21], 0x3000400
	s_mov_b64 s[22:23], 0x3000600
	s_mov_b64 s[24:25], 0x3000800
	s_mov_b64 s[26:27], 0x3000a00
	s_mov_b64 s[42:43], 0x3000c00
	s_mov_b64 s[44:45], 0x3000e00
	s_mov_b64 s[46:47], 0x3001000
	s_mov_b32 s39, 0x3001000
	s_mov_b32 s41, 0x7001000
	s_mov_b64 s[48:49], 0x3001200
	s_mov_b64 s[50:51], 0x3001400
	s_mov_b64 s[52:53], 0x3001600
	s_mov_b64 s[54:55], 0x3001800
	s_mov_b64 s[56:57], 0x3001a00
	s_mov_b64 s[58:59], 0x3001c00
	s_mov_b64 s[60:61], 0x3001e00
	v_mov_b32_e32 v79, 0
	v_mov_b32_e32 v100, 0x358637bd
	s_mov_b32 s66, 0x800000
	v_mbcnt_hi_u32_b32 v101, -1, v2
	s_mov_b32 s67, s40
	v_lshl_add_u64 v[214:215], v[0:1], 0, s[12:13]
	s_add_u32 s100, s64, s12
	s_addc_u32 s101, s65, s13
	v_add_co_u32_e32 v206, vcc, 0x3000000, v214
	s_nop 1
	v_addc_co_u32_e32 v207, vcc, 0, v215, vcc
	v_add_co_u32_e32 v208, vcc, 0x7000000, v214
	s_nop 1
	v_addc_co_u32_e32 v209, vcc, 0, v215, vcc
	v_add_co_u32_e32 v210, vcc, s39, v214
	s_nop 1
	v_addc_co_u32_e32 v211, vcc, 0, v215, vcc
	v_add_co_u32_e32 v212, vcc, s41, v214
	s_nop 1
	v_addc_co_u32_e32 v213, vcc, 0, v215, vcc
	global_load_dwordx2 v[198:199], v[208:209], off
	global_load_dwordx2 v[194:195], v[208:209], off offset:512
	global_load_dwordx2 v[192:193], v[208:209], off offset:1024
	global_load_dwordx2 v[188:189], v[208:209], off offset:1536
	global_load_dwordx2 v[184:185], v[208:209], off offset:2048
	global_load_dwordx2 v[182:183], v[208:209], off offset:2560
	global_load_dwordx2 v[178:179], v[208:209], off offset:3072
	global_load_dwordx2 v[170:171], v[210:211], off
	global_load_dwordx2 v[166:167], v[210:211], off offset:512
	global_load_dwordx2 v[160:161], v[210:211], off offset:1024
	global_load_dwordx2 v[156:157], v[210:211], off offset:1536
	global_load_dwordx2 v[172:173], v[212:213], off
	global_load_dwordx2 v[168:169], v[212:213], off offset:512
	global_load_dwordx2 v[162:163], v[212:213], off offset:1024
	global_load_dwordx2 v[158:159], v[212:213], off offset:1536
	global_load_dwordx2 v[174:175], v[208:209], off offset:3584
	global_load_dwordx2 v[152:153], v[210:211], off offset:2048
	global_load_dwordx2 v[148:149], v[210:211], off offset:2560
	global_load_dwordx2 v[144:145], v[210:211], off offset:3072
	global_load_dwordx2 v[140:141], v[210:211], off offset:3584
	global_load_dwordx2 v[154:155], v[212:213], off offset:2048
	global_load_dwordx2 v[150:151], v[212:213], off offset:2560
	global_load_dwordx2 v[146:147], v[212:213], off offset:3072
	global_load_dwordx2 v[142:143], v[212:213], off offset:3584
	global_load_dword v216, v79, s[100:101]
	global_load_dwordx2 v[204:205], v[206:207], off
	global_load_dwordx2 v[202:203], v[206:207], off offset:512
	global_load_dwordx2 v[200:201], v[206:207], off offset:1024
	global_load_dwordx2 v[196:197], v[206:207], off offset:1536
	global_load_dwordx2 v[190:191], v[206:207], off offset:2048
	global_load_dwordx2 v[186:187], v[206:207], off offset:2560
	global_load_dwordx2 v[180:181], v[206:207], off offset:3072
	global_load_dwordx2 v[176:177], v[206:207], off offset:3584
	s_waitcnt vmcnt(0)
	s_branch .Lnpf_body_3

; #define LAS __attribute__((address_space(3)))
; template <int MODE> ...
;     ...
;     LAS float* GP = (LAS float*)lds; LAS float* GN = (LAS float*)(lds + 16384); LAS float* GI = (LAS float*)(lds + 32768);
;     __syncthreads();
; #pragma unroll
;     for (int i = 0; i < 2; ++i) { const int o = 4 * (tid + NTHREADS * i);
;         if (MODE != 0) { *(LAS f32x4*)(GP + o) = *(const f32x4*)(gpost + o); const f32x4 g = *(const f32x4*)(gprev + o); *(LAS f32x4*)(GI + o) = (f32x4){1.f / g.x, 1.f / g.y, 1.f / g.z, 1.f / g.w}; }
;         if (MODE != 2) *(LAS f32x4*)(GN + o) = *(const f32x4*)(gpre + o); }
;     __syncthreads();
.LBB0_2327:
	s_cmp_gt_i32 s36, 22
	s_cselect_b64 s[6:7], -1, 0
	s_xor_b64 s[4:5], s[4:5], -1
	s_or_b64 s[4:5], s[6:7], s[4:5]
	s_and_b64 vcc, exec, s[4:5]
	s_cbranch_vccnz .LBB0_2333
	s_mov_b64 s[12:13], 0
	s_waitcnt vmcnt(0)
	v_mbcnt_lo_u32_b32 v2, -1, 0
	v_mbcnt_hi_u32_b32 v2, -1, v2
	s_load_dwordx4 s[4:7], s[0:1], 0x70
	s_load_dwordx2 s[8:9], s[0:1], 0xa8
	v_lshlrev_b32_e32 v0, 2, v2
	v_lshl_add_u32 v24, s89, 8, v0
	v_ashrrev_i32_e32 v25, 31, v24
	s_waitcnt lgkmcnt(0)
	s_add_u32 s4, s4, 0x4000
	s_addc_u32 s5, s5, 0
	v_lshlrev_b64 v[20:21], 2, v[24:25]
	v_lshl_add_u64 v[4:5], s[4:5], 0, v[20:21]
	v_add_u32_e32 v8, 0x800, v24
	s_barrier
	global_load_dwordx4 v[4:7], v[4:5], off
	v_ashrrev_i32_e32 v9, 31, v8
	v_lshlrev_b64 v[26:27], 2, v[8:9]
	v_lshl_add_u64 v[8:9], s[4:5], 0, v[26:27]
	s_add_u32 s4, s6, 0x4000
	s_addc_u32 s5, s7, 0
	s_add_u32 s6, s8, 0x4000
	v_lshl_add_u64 v[22:23], s[4:5], 0, v[20:21]
	global_load_dwordx4 v[8:11], v[8:9], off
	v_lshl_add_u64 v[28:29], s[4:5], 0, v[26:27]
	s_addc_u32 s7, s9, 0
	global_load_dwordx4 v[12:15], v[22:23], off
	global_load_dwordx4 v[16:19], v[28:29], off
	v_lshl_add_u64 v[20:21], s[6:7], 0, v[20:21]
	global_load_dwordx4 v[20:23], v[20:21], off
	v_lshl_add_u32 v1, v24, 2, 0
	v_lshl_add_u64 v[24:25], s[6:7], 0, v[26:27]
	global_load_dwordx4 v[24:27], v[24:25], off
	s_cmpk_gt_i32 s40, 0x1fff
	s_waitcnt vmcnt(3)
	ds_write_b128 v1, v[12:15]
	s_waitcnt vmcnt(2)
	ds_write_b128 v1, v[16:19] offset:8192
	s_waitcnt vmcnt(1)
	ds_write_b128 v1, v[20:23] offset:16384
	v_div_scale_f32 v3, s[4:5], v4, v4, 1.0
	v_div_scale_f32 v29, s[4:5], v5, v5, 1.0
	v_rcp_f32_e32 v37, v3
	v_div_scale_f32 v31, s[6:7], v6, v6, 1.0
	v_rcp_f32_e32 v38, v29
	v_div_scale_f32 v33, s[8:9], v7, v7, 1.0
	v_rcp_f32_e32 v39, v31
	v_rcp_f32_e32 v40, v33
	v_fma_f32 v12, -v3, v37, 1.0
	v_div_scale_f32 v28, vcc, 1.0, v4, 1.0
	v_fma_f32 v13, -v29, v38, 1.0
	v_fmac_f32_e32 v37, v12, v37
	v_div_scale_f32 v30, s[4:5], 1.0, v5, 1.0
	v_fma_f32 v14, -v31, v39, 1.0
	v_fmac_f32_e32 v38, v13, v38
	v_mul_f32_e32 v12, v28, v37
	v_div_scale_f32 v32, s[6:7], 1.0, v6, 1.0
	v_fma_f32 v15, -v33, v40, 1.0
	v_fmac_f32_e32 v39, v14, v39
	v_mul_f32_e32 v13, v30, v38
	v_fma_f32 v17, -v3, v12, v28
	v_div_scale_f32 v34, s[8:9], 1.0, v7, 1.0
	v_fmac_f32_e32 v40, v15, v40
	v_mul_f32_e32 v14, v32, v39
	v_fma_f32 v18, -v29, v13, v30
	v_fmac_f32_e32 v12, v17, v37
	v_div_scale_f32 v35, s[10:11], v8, v8, 1.0
	v_mul_f32_e32 v15, v34, v40
	v_fma_f32 v19, -v31, v14, v32
	v_fmac_f32_e32 v13, v18, v38
	v_fma_f32 v3, -v3, v12, v28
	v_rcp_f32_e32 v41, v35
	v_fma_f32 v20, -v33, v15, v34
	v_fmac_f32_e32 v14, v19, v39
	v_fma_f32 v17, -v29, v13, v30
	v_div_fmas_f32 v3, v3, v37, v12
	s_mov_b64 vcc, s[4:5]
	v_fmac_f32_e32 v15, v20, v40
	v_fma_f32 v18, -v31, v14, v32
	v_div_fixup_f32 v4, v3, v4, 1.0
	v_div_fmas_f32 v3, v17, v38, v13
	s_mov_b64 vcc, s[6:7]
	v_fma_f32 v19, -v33, v15, v34
	v_div_fixup_f32 v5, v3, v5, 1.0
	v_div_fmas_f32 v3, v18, v39, v14
	s_mov_b64 vcc, s[8:9]
	v_div_fixup_f32 v6, v3, v6, 1.0
	v_div_fmas_f32 v3, v19, v40, v15
	v_fma_f32 v16, -v35, v41, 1.0
	v_div_fixup_f32 v7, v3, v7, 1.0
	v_div_scale_f32 v3, s[4:5], v9, v9, 1.0
	v_div_scale_f32 v36, s[10:11], 1.0, v8, 1.0
	v_fmac_f32_e32 v41, v16, v41
	ds_write_b128 v1, v[4:7] offset:32768
	v_rcp_f32_e32 v5, v3
	v_mul_f32_e32 v16, v36, v41
	v_fma_f32 v21, -v35, v16, v36
	v_fmac_f32_e32 v16, v21, v41
	v_fma_f32 v20, -v35, v16, v36
	s_mov_b64 vcc, s[10:11]
	v_fma_f32 v6, -v3, v5, 1.0
	v_div_fmas_f32 v4, v20, v41, v16
	v_fmac_f32_e32 v5, v6, v5
	v_div_scale_f32 v6, vcc, 1.0, v9, 1.0
	v_mul_f32_e32 v7, v6, v5
	v_div_fixup_f32 v4, v4, v8, 1.0
	v_fma_f32 v8, -v3, v7, v6
	v_fmac_f32_e32 v7, v8, v5
	v_fma_f32 v3, -v3, v7, v6
	v_div_scale_f32 v6, s[4:5], v10, v10, 1.0
	v_rcp_f32_e32 v8, v6
	v_div_fmas_f32 v3, v3, v5, v7
	v_div_fixup_f32 v5, v3, v9, 1.0
	v_fma_f32 v3, -v6, v8, 1.0
	v_fmac_f32_e32 v8, v3, v8
	v_div_scale_f32 v3, vcc, 1.0, v10, 1.0
	v_mul_f32_e32 v7, v3, v8
	v_fma_f32 v9, -v6, v7, v3
	v_fmac_f32_e32 v7, v9, v8
	v_div_scale_f32 v9, s[4:5], v11, v11, 1.0
	v_rcp_f32_e32 v12, v9
	v_fma_f32 v3, -v6, v7, v3
	v_div_fmas_f32 v3, v3, v8, v7
	v_div_fixup_f32 v6, v3, v10, 1.0
	v_fma_f32 v3, -v9, v12, 1.0
	v_fmac_f32_e32 v12, v3, v12
	v_div_scale_f32 v3, vcc, 1.0, v11, 1.0
	v_mul_f32_e32 v7, v3, v12
	v_fma_f32 v8, -v9, v7, v3
	v_fmac_f32_e32 v7, v8, v12
	v_fma_f32 v3, -v9, v7, v3
	v_div_fmas_f32 v3, v3, v12, v7
	v_div_fixup_f32 v7, v3, v11, 1.0
	ds_write_b128 v1, v[4:7] offset:40960
	s_waitcnt vmcnt(0)
	ds_write_b128 v1, v[24:27] offset:24576
	s_waitcnt lgkmcnt(0)
	s_barrier
; #define LAS __attribute__((address_space(3)))
; __device__ __forceinline__ unsigned pk2(float lo, float hi) { const f32x2c v = {lo, hi}; return __builtin_bit_cast(unsigned, __builtin_convertvector(v, bf16x2c)); }
; template <int MODE> ...
;     ...
;     const int lo4 = 4 * lane;
; #pragma unroll 1
;     for (int row = gw; row < SEQ; row += NGW) {
;         asm volatile("" ::: "memory");
;         if (MODE == 0) {
;             const float* xr = xin + (size_t)row * DM; bf16* nw = xn_out + (size_t)row * DM;
;             f32x4 xv[16]; float ss = 0.f;
; #pragma unroll
;             for (int j = 0; j < 16; ++j) { xv[j] = *(const f32x4*)(xr + lo4 + 256 * j); ss += xv[j].x * xv[j].x + xv[j].y * xv[j].y + xv[j].z * xv[j].z + xv[j].w * xv[j].w; }
;             const float rstd = rsqrtf(wave_sum(ss) * (1.f / DM) + EPS);
;             if (lane == 0) rs_out[row] = rstd;
;             asm volatile("" ::: "memory");
; #pragma unroll
;             for (int j = 0; j < 16; ++j) { const f32x4 g = *(const LAS f32x4*)(GN + lo4 + 256 * j);
;                 v2u w; w.x = pk2(xv[j].x * rstd * g.x, xv[j].y * rstd * g.y); w.y = pk2(xv[j].z * rstd * g.z, xv[j].w * rstd * g.w);
;                 *(v2u*)(nw + lo4 + 256 * j) = w; }
;         } else {
;             const bf16* pr = xn + (size_t)row * DM; bf16* pw_out = xn_out + (size_t)row * DM; const bf16* hr = hb + (size_t)row * DM;
;             v2u pw[16], hw[16]; float ss = 0.f;
; #pragma unroll
;             for (int j = 0; j < 16; ++j) { pw[j] = *(const v2u*)(pr + lo4 + 256 * j); hw[j] = *(const v2u*)(hr + lo4 + 256 * j); }
	s_cbranch_scc1 .LBB0_2333
	s_load_dwordx2 s[6:7], s[0:1], 0xe8
	s_ashr_i32 s41, s40, 31
	s_lshl_b64 s[8:9], s[40:41], 2
	v_ashrrev_i32_e32 v1, 31, v0
	v_cmp_eq_u32_e64 s[4:5], 0, v2
	s_waitcnt lgkmcnt(0)
	s_add_u32 s8, s6, s8
	s_addc_u32 s9, s7, s9
	s_add_u32 s64, s8, 0x2c0000
	s_addc_u32 s65, s9, 0
	s_ashr_i32 s39, s38, 31
	s_lshl_b64 s[8:9], s[38:39], 2
	s_lshl_b64 s[10:11], s[40:41], 13
	s_add_u32 s6, s6, s10
	s_addc_u32 s7, s7, s11
	v_mbcnt_lo_u32_b32 v2, -1, 0
	v_lshl_add_u32 v71, v0, 2, 0
	v_lshl_add_u64 v[0:1], v[0:1], 1, s[6:7]
	s_lshl_b64 s[10:11], s[38:39], 13
	s_mov_b64 s[14:15], 0x3000000
	s_mov_b64 s[18:19], 0x3000200
	s_mov_b64 s[20:21], 0x3000400
	s_mov_b64 s[22:23], 0x3000600
	s_mov_b64 s[24:25], 0x3000800
	s_mov_b64 s[26:27], 0x3000a00
	s_mov_b64 s[42:43], 0x3000c00
	s_mov_b64 s[44:45], 0x3000e00
	s_mov_b64 s[46:47], 0x3001000
	s_mov_b32 s39, 0x3001000
	s_mov_b32 s41, 0x7001000
	s_mov_b64 s[48:49], 0x3001200
	s_mov_b64 s[50:51], 0x3001400
	s_mov_b64 s[52:53], 0x3001600
	s_mov_b64 s[54:55], 0x3001800
	s_mov_b64 s[56:57], 0x3001a00
	s_mov_b64 s[58:59], 0x3001c00
	s_mov_b64 s[60:61], 0x3001e00
	v_mov_b32_e32 v98, 0
	v_mov_b32_e32 v99, 0x358637bd
	s_mov_b32 s66, 0x800000
	v_mbcnt_hi_u32_b32 v100, -1, v2
	s_mov_b32 s67, s40
	v_lshl_add_u64 v[214:215], v[0:1], 0, s[12:13]
	s_add_u32 s100, s64, s12
	s_addc_u32 s101, s65, s13
	v_add_co_u32_e32 v206, vcc, 0x3000000, v214
	s_nop 1
	v_addc_co_u32_e32 v207, vcc, 0, v215, vcc
	v_add_co_u32_e32 v208, vcc, 0x7000000, v214
	s_nop 1
	v_addc_co_u32_e32 v209, vcc, 0, v215, vcc
	v_add_co_u32_e32 v210, vcc, s39, v214
	s_nop 1
	v_addc_co_u32_e32 v211, vcc, 0, v215, vcc
	v_add_co_u32_e32 v212, vcc, s41, v214
	s_nop 1
	v_addc_co_u32_e32 v213, vcc, 0, v215, vcc
	global_load_dwordx2 v[198:199], v[208:209], off
	global_load_dwordx2 v[192:193], v[208:209], off offset:512
	global_load_dwordx2 v[190:191], v[208:209], off offset:1024
	global_load_dwordx2 v[186:187], v[208:209], off offset:1536
	global_load_dwordx2 v[182:183], v[208:209], off offset:2048
	global_load_dwordx2 v[180:181], v[208:209], off offset:2560
	global_load_dwordx2 v[176:177], v[208:209], off offset:3072
	global_load_dwordx2 v[168:169], v[210:211], off
	global_load_dwordx2 v[164:165], v[210:211], off offset:512
	global_load_dwordx2 v[160:161], v[210:211], off offset:1024
	global_load_dwordx2 v[156:157], v[210:211], off offset:1536
	global_load_dwordx2 v[170:171], v[212:213], off
	global_load_dwordx2 v[166:167], v[212:213], off offset:512
	global_load_dwordx2 v[162:163], v[212:213], off offset:1024
	global_load_dwordx2 v[158:159], v[212:213], off offset:1536
	global_load_dwordx2 v[172:173], v[208:209], off offset:3584
	global_load_dwordx2 v[152:153], v[210:211], off offset:2048
	global_load_dwordx2 v[148:149], v[210:211], off offset:2560
	global_load_dwordx2 v[144:145], v[210:211], off offset:3072
	global_load_dwordx2 v[140:141], v[210:211], off offset:3584
	global_load_dwordx2 v[154:155], v[212:213], off offset:2048
	global_load_dwordx2 v[150:151], v[212:213], off offset:2560
	global_load_dwordx2 v[146:147], v[212:213], off offset:3072
	global_load_dwordx2 v[142:143], v[212:213], off offset:3584
	global_load_dword v216, v98, s[100:101]
	global_load_dwordx2 v[202:203], v[206:207], off
	global_load_dwordx2 v[200:201], v[206:207], off offset:512
	global_load_dwordx2 v[196:197], v[206:207], off offset:1024
	global_load_dwordx2 v[194:195], v[206:207], off offset:1536
	global_load_dwordx2 v[188:189], v[206:207], off offset:2048
	global_load_dwordx2 v[184:185], v[206:207], off offset:2560
	global_load_dwordx2 v[178:179], v[206:207], off offset:3072
	global_load_dwordx2 v[174:175], v[206:207], off offset:3584
	s_waitcnt vmcnt(0)
	s_branch .Lnpf_body_4

; __global__ void __launch_bounds__(NTHREADS, 2) mk_fwd(Args args) {
	.amdhsa_kernel _Z6mk_fwd4Args
		.amdhsa_group_segment_fixed_size 0
		.amdhsa_private_segment_fixed_size 0
		.amdhsa_kernarg_size 504
		.amdhsa_user_sgpr_count 2
		.amdhsa_user_sgpr_dispatch_ptr 0
		.amdhsa_user_sgpr_queue_ptr 0
		.amdhsa_user_sgpr_kernarg_segment_ptr 1
		.amdhsa_user_sgpr_dispatch_id 0
		.amdhsa_user_sgpr_kernarg_preload_length 0
		.amdhsa_user_sgpr_kernarg_preload_offset 0
		.amdhsa_user_sgpr_private_segment_size 0
		.amdhsa_uses_dynamic_stack 0
		.amdhsa_enable_private_segment 0
		.amdhsa_system_sgpr_workgroup_id_x 1
		.amdhsa_system_sgpr_workgroup_id_y 0
		.amdhsa_system_sgpr_workgroup_id_z 0
		.amdhsa_system_sgpr_workgroup_info 0
		.amdhsa_system_vgpr_workitem_id 0
		.amdhsa_next_free_vgpr 255
		.amdhsa_next_free_sgpr 102
		.amdhsa_accum_offset 256
		.amdhsa_reserve_vcc 1
		.amdhsa_float_round_mode_32 0
		.amdhsa_float_round_mode_16_64 0
		.amdhsa_float_denorm_mode_32 3
		.amdhsa_float_denorm_mode_16_64 3
		.amdhsa_dx10_clamp 1
		.amdhsa_ieee_mode 1
		.amdhsa_fp16_overflow 0
		.amdhsa_tg_split 0
		.amdhsa_exception_fp_ieee_invalid_op 0
		.amdhsa_exception_fp_denorm_src 0
		.amdhsa_exception_fp_ieee_div_zero 0
		.amdhsa_exception_fp_ieee_overflow 0
		.amdhsa_exception_fp_ieee_underflow 0
		.amdhsa_exception_fp_ieee_inexact 0
		.amdhsa_exception_int_div_zero 0
	.end_amdhsa_kernel

; __global__ void __launch_bounds__(NTHREADS, 2) mk_fwd(Args args) {
amdhsa.kernels:
  - .agpr_count:     0
    .args:
      - .offset:         0
        .size:           248
        .value_kind:     by_value
      - .offset:         248
        .size:           4
        .value_kind:     hidden_block_count_x
      - .offset:         252
        .size:           4
        .value_kind:     hidden_block_count_y
      - .offset:         256
        .size:           4
        .value_kind:     hidden_block_count_z
      - .offset:         260
        .size:           2
        .value_kind:     hidden_group_size_x
      - .offset:         262
        .size:           2
        .value_kind:     hidden_group_size_y
      - .offset:         264
        .size:           2
        .value_kind:     hidden_group_size_z
      - .offset:         266
        .size:           2
        .value_kind:     hidden_remainder_x
      - .offset:         268
        .size:           2
        .value_kind:     hidden_remainder_y
      - .offset:         270
        .size:           2
        .value_kind:     hidden_remainder_z
      - .offset:         288
        .size:           8
        .value_kind:     hidden_global_offset_x
      - .offset:         296
        .size:           8
        .value_kind:     hidden_global_offset_y
      - .offset:         304
        .size:           8
        .value_kind:     hidden_global_offset_z
      - .offset:         312
        .size:           2
        .value_kind:     hidden_grid_dims
      - .offset:         368
        .size:           4
        .value_kind:     hidden_dynamic_lds_size
    .group_segment_fixed_size: 0
    .kernarg_segment_align: 8
    .kernarg_segment_size: 504
    .language:       OpenCL C
    .language_version:
      - 2
      - 0
    .max_flat_workgroup_size: 512
    .name:           _Z6mk_fwd4Args
    .private_segment_fixed_size: 0
    .sgpr_count:     108
    .sgpr_spill_count: 2
    .symbol:         _Z6mk_fwd4Args.kd
    .uniform_work_group_size: 1
    .uses_dynamic_stack: false
    .vgpr_count:     255
    .vgpr_spill_count: 0
    .wavefront_size: 64
